# GEMM K-loop heads and the MLA tile loop head aligned to 64 bytes (p2align 6), otherwise v38
# baseline (speedup 1.0000x reference)
;     __device__ bool next(int i, Unit& u) const { Unit b; if (!base.next(i / 3, b)) return false; u.pm = b.pm; u.pn = b.pn + 4 * (i % 3); return true; }
;     __device__ bool next(int i, Unit& u) const { Unit b; if (!base.next(i / 3, b)) return false; const int br = i % 3; u.pm = b.pm + 64 * br; u.pn = b.pn + 4 * br; return true; }
; template <class Epi, class Sched, bool ALIGN_EPI = false, bool SP2 = false>
; __device__ __forceinline__ void gemm_phase(PG8_LAS unsigned char* lds, const Gemm g, const Sched& S, const Epi& E) {
;     ...
;         const bool has_next = S.next(ui + 1, nxt);
;         const char* nA = has_next ? (const char*)g.A + (size_t)nxt.pm * tstep : cA; const char* nB = has_next ? (const char*)g.Bt + (size_t)nxt.pn * tstep : cB;
;         for (int t = 0; t < nt; t += 2) {
;             const bool last = (t == nt - 2);
;             const char* a1 = cA + (size_t)(t + 1) * kstep;
;             const char* a2 = last ? nA : cA + (size_t)(t + 2) * kstep; const char* b2 = last ? nB : cB + (size_t)(t + 2) * kstep;
;             const char* a3 = a2 + kstep; const char* b3 = b2 + kstep;
;     ...
; #pragma unroll
;         for (int a = 0; a < 2; ++a)
; #pragma unroll
;             for (int b = 0; b < 2; ++b)
; #pragma unroll
;                 for (int m = 0; m < 4; ++m)
; #pragma unroll
;                     for (int n = 0; n < 2; ++n) acc[a][b][m][n] = (f32x4){0.f, 0.f, 0.f, 0.f};
;         cur = nxt; cA = nA; cB = nB; ++ui;
.LBB0_321:
	s_ashr_i32 s43, s42, 31
	s_lshl_b64 s[12:13], s[42:43], 19
	s_add_u32 s58, s36, s12
	s_addc_u32 s59, s37, s13
	s_and_b64 s[12:13], s[2:3], exec
	s_cselect_b32 s12, s59, s75
	s_cselect_b32 s13, s58, s74
	s_ashr_i32 s35, s34, 31
	s_lshl_b64 s[60:61], s[34:35], 19
	s_add_u32 s60, s4, s60
	s_addc_u32 s61, s5, s61
	s_and_b64 s[76:77], s[2:3], exec
	s_cselect_b32 s35, s61, s71
	s_cselect_b32 s43, s60, s70
	s_add_u32 s89, s70, 0x100
	s_addc_u32 s90, s71, 0
	s_add_u32 s70, s74, 0x40080
	v_mov_b32_e32 v0, 0
	s_addc_u32 s71, s75, 0
	s_mov_b32 s91, -2
	v_mov_b32_e32 v1, v0
	v_mov_b32_e32 v2, v0
	v_mov_b32_e32 v3, v0
	v_mov_b32_e32 v4, v0
	v_mov_b32_e32 v5, v0
	v_mov_b32_e32 v6, v0
	v_mov_b32_e32 v7, v0
	v_mov_b32_e32 v16, v0
	v_mov_b32_e32 v17, v0
	v_mov_b32_e32 v18, v0
	v_mov_b32_e32 v19, v0
	v_mov_b32_e32 v20, v0
	v_mov_b32_e32 v21, v0
	v_mov_b32_e32 v22, v0
	v_mov_b32_e32 v23, v0
	v_mov_b32_e32 v32, v0
	v_mov_b32_e32 v33, v0
	v_mov_b32_e32 v34, v0
	v_mov_b32_e32 v35, v0
	v_mov_b32_e32 v36, v0
	v_mov_b32_e32 v37, v0
	v_mov_b32_e32 v38, v0
	v_mov_b32_e32 v39, v0
	v_mov_b32_e32 v48, v0
	v_mov_b32_e32 v49, v0
	v_mov_b32_e32 v50, v0
	v_mov_b32_e32 v51, v0
	v_mov_b32_e32 v52, v0
	v_mov_b32_e32 v53, v0
	v_mov_b32_e32 v54, v0
	v_mov_b32_e32 v55, v0
	v_mov_b32_e32 v8, v0
	v_mov_b32_e32 v9, v0
	v_mov_b32_e32 v10, v0
	v_mov_b32_e32 v11, v0
	v_mov_b32_e32 v12, v0
	v_mov_b32_e32 v13, v0
	v_mov_b32_e32 v14, v0
	v_mov_b32_e32 v15, v0
	v_mov_b32_e32 v24, v0
	v_mov_b32_e32 v25, v0
	v_mov_b32_e32 v26, v0
	v_mov_b32_e32 v27, v0
	v_mov_b32_e32 v28, v0
	v_mov_b32_e32 v29, v0
	v_mov_b32_e32 v30, v0
	v_mov_b32_e32 v31, v0
	v_mov_b32_e32 v40, v0
	v_mov_b32_e32 v41, v0
	v_mov_b32_e32 v42, v0
	v_mov_b32_e32 v43, v0
	v_mov_b32_e32 v44, v0
	v_mov_b32_e32 v45, v0
	v_mov_b32_e32 v46, v0
	v_mov_b32_e32 v47, v0
	v_mov_b32_e32 v56, v0
	v_mov_b32_e32 v57, v0
	v_mov_b32_e32 v58, v0
	v_mov_b32_e32 v59, v0
	v_mov_b32_e32 v60, v0
	v_mov_b32_e32 v61, v0
	v_mov_b32_e32 v62, v0
	v_mov_b32_e32 v63, v0
	v_mov_b32_e32 v64, v0
	v_mov_b32_e32 v65, v0
	v_mov_b32_e32 v66, v0
	v_mov_b32_e32 v67, v0
	v_mov_b32_e32 v68, v0
	v_mov_b32_e32 v69, v0
	v_mov_b32_e32 v70, v0
	v_mov_b32_e32 v71, v0
	v_mov_b32_e32 v80, v0
	v_mov_b32_e32 v81, v0
	v_mov_b32_e32 v82, v0
	v_mov_b32_e32 v83, v0
	v_mov_b32_e32 v84, v0
	v_mov_b32_e32 v85, v0
	v_mov_b32_e32 v86, v0
	v_mov_b32_e32 v87, v0
	v_mov_b32_e32 v96, v0
	v_mov_b32_e32 v97, v0
	v_mov_b32_e32 v98, v0
	v_mov_b32_e32 v99, v0
	v_mov_b32_e32 v100, v0
	v_mov_b32_e32 v101, v0
	v_mov_b32_e32 v102, v0
	v_mov_b32_e32 v103, v0
	v_mov_b32_e32 v112, v0
	v_mov_b32_e32 v113, v0
	v_mov_b32_e32 v114, v0
	v_mov_b32_e32 v115, v0
	v_mov_b32_e32 v116, v0
	v_mov_b32_e32 v117, v0
	v_mov_b32_e32 v118, v0
	v_mov_b32_e32 v119, v0
	v_mov_b32_e32 v72, v0
	v_mov_b32_e32 v73, v0
	v_mov_b32_e32 v74, v0
	v_mov_b32_e32 v75, v0
	v_mov_b32_e32 v76, v0
	v_mov_b32_e32 v77, v0
	v_mov_b32_e32 v78, v0
	v_mov_b32_e32 v79, v0
	v_mov_b32_e32 v88, v0
	v_mov_b32_e32 v89, v0
	v_mov_b32_e32 v90, v0
	v_mov_b32_e32 v91, v0
	v_mov_b32_e32 v92, v0
	v_mov_b32_e32 v93, v0
	v_mov_b32_e32 v94, v0
	v_mov_b32_e32 v95, v0
	v_mov_b32_e32 v104, v0
	v_mov_b32_e32 v105, v0
	v_mov_b32_e32 v106, v0
	v_mov_b32_e32 v107, v0
	v_mov_b32_e32 v108, v0
	v_mov_b32_e32 v109, v0
	v_mov_b32_e32 v110, v0
	v_mov_b32_e32 v111, v0
	v_mov_b32_e32 v120, v0
	v_mov_b32_e32 v121, v0
	v_mov_b32_e32 v122, v0
	v_mov_b32_e32 v123, v0
	v_mov_b32_e32 v124, v0
	v_mov_b32_e32 v125, v0
	v_mov_b32_e32 v126, v0
	v_mov_b32_e32 v127, v0
	.p2align 6

;     __device__ bool next(int i, Unit& u) const { Unit b; if (!base.next(i / 3, b)) return false; u.pm = b.pm; u.pn = b.pn + 4 * (i % 3); return true; }
;     __device__ bool next(int i, Unit& u) const { Unit b; if (!base.next(i / 3, b)) return false; const int br = i % 3; u.pm = b.pm + 64 * br; u.pn = b.pn + 4 * br; return true; }
; template <class Epi, class Sched, bool ALIGN_EPI = false, bool SP2 = false>
; __device__ __forceinline__ void gemm_phase(PG8_LAS unsigned char* lds, const Gemm g, const Sched& S, const Epi& E) {
;     ...
;         const bool has_next = S.next(ui + 1, nxt);
;         const char* nA = has_next ? (const char*)g.A + (size_t)nxt.pm * tstep : cA; const char* nB = has_next ? (const char*)g.Bt + (size_t)nxt.pn * tstep : cB;
;         for (int t = 0; t < nt; t += 2) {
;             const bool last = (t == nt - 2);
;             const char* a1 = cA + (size_t)(t + 1) * kstep;
;             const char* a2 = last ? nA : cA + (size_t)(t + 2) * kstep; const char* b2 = last ? nB : cB + (size_t)(t + 2) * kstep;
;             const char* a3 = a2 + kstep; const char* b3 = b2 + kstep;
;     ...
; #pragma unroll
;         for (int a = 0; a < 2; ++a)
; #pragma unroll
;             for (int b = 0; b < 2; ++b)
; #pragma unroll
;                 for (int m = 0; m < 4; ++m)
; #pragma unroll
;                     for (int n = 0; n < 2; ++n) acc[a][b][m][n] = (f32x4){0.f, 0.f, 0.f, 0.f};
;         cur = nxt; cA = nA; cB = nB; ++ui;
.LBB0_337:
	s_ashr_i32 s43, s42, 31
	s_lshl_b64 s[12:13], s[42:43], 19
	s_add_u32 s60, s37, s12
	s_addc_u32 s61, s38, s13
	s_and_b64 s[12:13], s[58:59], exec
	s_cselect_b32 s12, s61, s75
	s_cselect_b32 s13, s60, s74
	s_ashr_i32 s35, s34, 31
	s_lshl_b64 s[68:69], s[34:35], 19
	s_add_u32 s68, s39, s68
	s_addc_u32 s69, s40, s69
	s_and_b64 s[76:77], s[58:59], exec
	s_cselect_b32 s35, s69, s71
	s_cselect_b32 s43, s68, s70
	s_add_u32 s90, s70, 0x100
	s_addc_u32 s91, s71, 0
	s_add_u32 s70, s74, 0x40080
	v_mov_b32_e32 v0, 0
	s_addc_u32 s71, s75, 0
	s_mov_b32 s92, -2
	v_mov_b32_e32 v1, v0
	v_mov_b32_e32 v2, v0
	v_mov_b32_e32 v3, v0
	v_mov_b32_e32 v4, v0
	v_mov_b32_e32 v5, v0
	v_mov_b32_e32 v6, v0
	v_mov_b32_e32 v7, v0
	v_mov_b32_e32 v8, v0
	v_mov_b32_e32 v9, v0
	v_mov_b32_e32 v10, v0
	v_mov_b32_e32 v11, v0
	v_mov_b32_e32 v12, v0
	v_mov_b32_e32 v13, v0
	v_mov_b32_e32 v14, v0
	v_mov_b32_e32 v15, v0
	v_mov_b32_e32 v24, v0
	v_mov_b32_e32 v25, v0
	v_mov_b32_e32 v26, v0
	v_mov_b32_e32 v27, v0
	v_mov_b32_e32 v28, v0
	v_mov_b32_e32 v29, v0
	v_mov_b32_e32 v30, v0
	v_mov_b32_e32 v31, v0
	v_mov_b32_e32 v40, v0
	v_mov_b32_e32 v41, v0
	v_mov_b32_e32 v42, v0
	v_mov_b32_e32 v43, v0
	v_mov_b32_e32 v44, v0
	v_mov_b32_e32 v45, v0
	v_mov_b32_e32 v46, v0
	v_mov_b32_e32 v47, v0
	v_mov_b32_e32 v16, v0
	v_mov_b32_e32 v17, v0
	v_mov_b32_e32 v18, v0
	v_mov_b32_e32 v19, v0
	v_mov_b32_e32 v20, v0
	v_mov_b32_e32 v21, v0
	v_mov_b32_e32 v22, v0
	v_mov_b32_e32 v23, v0
	v_mov_b32_e32 v32, v0
	v_mov_b32_e32 v33, v0
	v_mov_b32_e32 v34, v0
	v_mov_b32_e32 v35, v0
	v_mov_b32_e32 v36, v0
	v_mov_b32_e32 v37, v0
	v_mov_b32_e32 v38, v0
	v_mov_b32_e32 v39, v0
	v_mov_b32_e32 v48, v0
	v_mov_b32_e32 v49, v0
	v_mov_b32_e32 v50, v0
	v_mov_b32_e32 v51, v0
	v_mov_b32_e32 v52, v0
	v_mov_b32_e32 v53, v0
	v_mov_b32_e32 v54, v0
	v_mov_b32_e32 v55, v0
	v_mov_b32_e32 v56, v0
	v_mov_b32_e32 v57, v0
	v_mov_b32_e32 v58, v0
	v_mov_b32_e32 v59, v0
	v_mov_b32_e32 v60, v0
	v_mov_b32_e32 v61, v0
	v_mov_b32_e32 v62, v0
	v_mov_b32_e32 v63, v0
	v_mov_b32_e32 v64, v0
	v_mov_b32_e32 v65, v0
	v_mov_b32_e32 v66, v0
	v_mov_b32_e32 v67, v0
	v_mov_b32_e32 v68, v0
	v_mov_b32_e32 v69, v0
	v_mov_b32_e32 v70, v0
	v_mov_b32_e32 v71, v0
	v_mov_b32_e32 v72, v0
	v_mov_b32_e32 v73, v0
	v_mov_b32_e32 v74, v0
	v_mov_b32_e32 v75, v0
	v_mov_b32_e32 v76, v0
	v_mov_b32_e32 v77, v0
	v_mov_b32_e32 v78, v0
	v_mov_b32_e32 v79, v0
	v_mov_b32_e32 v84, v0
	v_mov_b32_e32 v85, v0
	v_mov_b32_e32 v86, v0
	v_mov_b32_e32 v87, v0
	v_mov_b32_e32 v92, v0
	v_mov_b32_e32 v93, v0
	v_mov_b32_e32 v94, v0
	v_mov_b32_e32 v95, v0
	v_mov_b32_e32 v100, v0
	v_mov_b32_e32 v101, v0
	v_mov_b32_e32 v102, v0
	v_mov_b32_e32 v103, v0
	v_mov_b32_e32 v108, v0
	v_mov_b32_e32 v109, v0
	v_mov_b32_e32 v110, v0
	v_mov_b32_e32 v111, v0
	v_mov_b32_e32 v80, v0
	v_mov_b32_e32 v81, v0
	v_mov_b32_e32 v82, v0
	v_mov_b32_e32 v83, v0
	v_mov_b32_e32 v88, v0
	v_mov_b32_e32 v89, v0
	v_mov_b32_e32 v90, v0
	v_mov_b32_e32 v91, v0
	v_mov_b32_e32 v96, v0
	v_mov_b32_e32 v97, v0
	v_mov_b32_e32 v98, v0
	v_mov_b32_e32 v99, v0
	v_mov_b32_e32 v104, v0
	v_mov_b32_e32 v105, v0
	v_mov_b32_e32 v106, v0
	v_mov_b32_e32 v107, v0
	v_mov_b32_e32 v112, v0
	v_mov_b32_e32 v113, v0
	v_mov_b32_e32 v114, v0
	v_mov_b32_e32 v115, v0
	v_mov_b32_e32 v116, v0
	v_mov_b32_e32 v117, v0
	v_mov_b32_e32 v118, v0
	v_mov_b32_e32 v119, v0
	v_mov_b32_e32 v120, v0
	v_mov_b32_e32 v121, v0
	v_mov_b32_e32 v122, v0
	v_mov_b32_e32 v123, v0
	v_mov_b32_e32 v124, v0
	v_mov_b32_e32 v125, v0
	v_mov_b32_e32 v126, v0
	v_mov_b32_e32 v127, v0
	.p2align 6

; template <class Epi, class Sched, bool ALIGN_EPI = false, bool SP2 = false>
; __device__ __forceinline__ void gemm_phase(PG8_LAS unsigned char* lds, const Gemm g, const Sched& S, const Epi& E) {
;     ...
;         for (int t = 0; t < nt; t += 2) {
;             const bool last = (t == nt - 2);
;             const char* a1 = cA + (size_t)(t + 1) * kstep;
;             const char* a2 = last ? nA : cA + (size_t)(t + 2) * kstep; const char* b2 = last ? nB : cB + (size_t)(t + 2) * kstep;
;             const char* a3 = a2 + kstep; const char* b3 = b2 + kstep;
;     ...
; #pragma unroll
;         for (int a = 0; a < 2; ++a)
; #pragma unroll
;             for (int b = 0; b < 2; ++b)
; #pragma unroll
;                 for (int m = 0; m < 4; ++m)
; #pragma unroll
;                     for (int n = 0; n < 2; ++n) acc[a][b][m][n] = (f32x4){0.f, 0.f, 0.f, 0.f};
;         cur = nxt; cA = nA; cB = nB; ++ui;
.LBB0_541:
	s_add_u32 s88, s52, 0x100
	s_addc_u32 s89, s53, 0
	s_add_u32 s52, s58, 0xb0080
	v_mov_b32_e32 v0, 0
	s_addc_u32 s53, s59, 0
	s_mov_b32 s90, -2
	s_waitcnt lgkmcnt(0)
	v_mov_b32_e32 v1, v0
	v_mov_b32_e32 v2, v0
	v_mov_b32_e32 v3, v0
	v_mov_b32_e32 v4, v0
	v_mov_b32_e32 v5, v0
	v_mov_b32_e32 v6, v0
	v_mov_b32_e32 v7, v0
	v_mov_b32_e32 v16, v0
	v_mov_b32_e32 v17, v0
	v_mov_b32_e32 v18, v0
	v_mov_b32_e32 v19, v0
	v_mov_b32_e32 v20, v0
	v_mov_b32_e32 v21, v0
	v_mov_b32_e32 v22, v0
	v_mov_b32_e32 v23, v0
	v_mov_b32_e32 v32, v0
	v_mov_b32_e32 v33, v0
	v_mov_b32_e32 v34, v0
	v_mov_b32_e32 v35, v0
	v_mov_b32_e32 v36, v0
	v_mov_b32_e32 v37, v0
	v_mov_b32_e32 v38, v0
	v_mov_b32_e32 v39, v0
	v_mov_b32_e32 v48, v0
	v_mov_b32_e32 v49, v0
	v_mov_b32_e32 v50, v0
	v_mov_b32_e32 v51, v0
	v_mov_b32_e32 v52, v0
	v_mov_b32_e32 v53, v0
	v_mov_b32_e32 v54, v0
	v_mov_b32_e32 v55, v0
	v_mov_b32_e32 v8, v0
	v_mov_b32_e32 v9, v0
	v_mov_b32_e32 v10, v0
	v_mov_b32_e32 v11, v0
	v_mov_b32_e32 v12, v0
	v_mov_b32_e32 v13, v0
	v_mov_b32_e32 v14, v0
	v_mov_b32_e32 v15, v0
	v_mov_b32_e32 v24, v0
	v_mov_b32_e32 v25, v0
	v_mov_b32_e32 v26, v0
	v_mov_b32_e32 v27, v0
	v_mov_b32_e32 v28, v0
	v_mov_b32_e32 v29, v0
	v_mov_b32_e32 v30, v0
	v_mov_b32_e32 v31, v0
	v_mov_b32_e32 v40, v0
	v_mov_b32_e32 v41, v0
	v_mov_b32_e32 v42, v0
	v_mov_b32_e32 v43, v0
	v_mov_b32_e32 v44, v0
	v_mov_b32_e32 v45, v0
	v_mov_b32_e32 v46, v0
	v_mov_b32_e32 v47, v0
	v_mov_b32_e32 v56, v0
	v_mov_b32_e32 v57, v0
	v_mov_b32_e32 v58, v0
	v_mov_b32_e32 v59, v0
	v_mov_b32_e32 v60, v0
	v_mov_b32_e32 v61, v0
	v_mov_b32_e32 v62, v0
	v_mov_b32_e32 v63, v0
	v_mov_b32_e32 v64, v0
	v_mov_b32_e32 v65, v0
	v_mov_b32_e32 v66, v0
	v_mov_b32_e32 v67, v0
	v_mov_b32_e32 v68, v0
	v_mov_b32_e32 v69, v0
	v_mov_b32_e32 v70, v0
	v_mov_b32_e32 v71, v0
	v_mov_b32_e32 v80, v0
	v_mov_b32_e32 v81, v0
	v_mov_b32_e32 v82, v0
	v_mov_b32_e32 v83, v0
	v_mov_b32_e32 v84, v0
	v_mov_b32_e32 v85, v0
	v_mov_b32_e32 v86, v0
	v_mov_b32_e32 v87, v0
	v_mov_b32_e32 v96, v0
	v_mov_b32_e32 v97, v0
	v_mov_b32_e32 v98, v0
	v_mov_b32_e32 v99, v0
	v_mov_b32_e32 v100, v0
	v_mov_b32_e32 v101, v0
	v_mov_b32_e32 v102, v0
	v_mov_b32_e32 v103, v0
	v_mov_b32_e32 v112, v0
	v_mov_b32_e32 v113, v0
	v_mov_b32_e32 v114, v0
	v_mov_b32_e32 v115, v0
	v_mov_b32_e32 v116, v0
	v_mov_b32_e32 v117, v0
	v_mov_b32_e32 v118, v0
	v_mov_b32_e32 v119, v0
	v_mov_b32_e32 v72, v0
	v_mov_b32_e32 v73, v0
	v_mov_b32_e32 v74, v0
	v_mov_b32_e32 v75, v0
	v_mov_b32_e32 v76, v0
	v_mov_b32_e32 v77, v0
	v_mov_b32_e32 v78, v0
	v_mov_b32_e32 v79, v0
	v_mov_b32_e32 v88, v0
	v_mov_b32_e32 v89, v0
	v_mov_b32_e32 v90, v0
	v_mov_b32_e32 v91, v0
	v_mov_b32_e32 v92, v0
	v_mov_b32_e32 v93, v0
	v_mov_b32_e32 v94, v0
	v_mov_b32_e32 v95, v0
	v_mov_b32_e32 v104, v0
	v_mov_b32_e32 v105, v0
	v_mov_b32_e32 v106, v0
	v_mov_b32_e32 v107, v0
	v_mov_b32_e32 v108, v0
	v_mov_b32_e32 v109, v0
	v_mov_b32_e32 v110, v0
	v_mov_b32_e32 v111, v0
	v_mov_b32_e32 v120, v0
	v_mov_b32_e32 v121, v0
	v_mov_b32_e32 v122, v0
	v_mov_b32_e32 v123, v0
	v_mov_b32_e32 v124, v0
	v_mov_b32_e32 v125, v0
	v_mov_b32_e32 v126, v0
	v_mov_b32_e32 v127, v0
	.p2align 6

;     __device__ bool next(int i, Unit& u) const { Unit b; if (!base.next(i / 3, b)) return false; u.pm = b.pm; u.pn = b.pn + 4 * (i % 3); return true; }
;     __device__ bool next(int i, Unit& u) const { Unit b; if (!base.next(i / 3, b)) return false; const int br = i % 3; u.pm = b.pm + 64 * br; u.pn = b.pn + 4 * br; return true; }
; template <class Epi, class Sched, bool ALIGN_EPI = false, bool SP2 = false>
; __device__ __forceinline__ void gemm_phase(PG8_LAS unsigned char* lds, const Gemm g, const Sched& S, const Epi& E) {
;     ...
;         const bool has_next = S.next(ui + 1, nxt);
;         const char* nA = has_next ? (const char*)g.A + (size_t)nxt.pm * tstep : cA; const char* nB = has_next ? (const char*)g.Bt + (size_t)nxt.pn * tstep : cB;
;         for (int t = 0; t < nt; t += 2) {
;             const bool last = (t == nt - 2);
;             const char* a1 = cA + (size_t)(t + 1) * kstep;
;             const char* a2 = last ? nA : cA + (size_t)(t + 2) * kstep; const char* b2 = last ? nB : cB + (size_t)(t + 2) * kstep;
;             const char* a3 = a2 + kstep; const char* b3 = b2 + kstep;
;     ...
; #pragma unroll
;         for (int a = 0; a < 2; ++a)
; #pragma unroll
;             for (int b = 0; b < 2; ++b)
; #pragma unroll
;                 for (int m = 0; m < 4; ++m)
; #pragma unroll
;                     for (int n = 0; n < 2; ++n) acc[a][b][m][n] = (f32x4){0.f, 0.f, 0.f, 0.f};
;         cur = nxt; cA = nA; cB = nB; ++ui;
.LBB0_631:
	s_ashr_i32 s69, s68, 31
	s_lshl_b64 s[12:13], s[68:69], 19
	v_readlane_b32 s7, v248, 2
	s_add_u32 s76, s7, s12
	v_readlane_b32 s7, v248, 3
	s_addc_u32 s77, s7, s13
	s_and_b64 s[12:13], s[4:5], exec
	s_cselect_b32 s7, s77, s11
	s_cselect_b32 s12, s76, s10
	s_ashr_i32 s89, s88, 31
	s_lshl_b64 s[38:39], s[88:89], 19
	v_readlane_b32 s13, v249, 61
	s_add_u32 s78, s13, s38
	v_readlane_b32 s13, v249, 62
	s_addc_u32 s79, s13, s39
	s_and_b64 s[38:39], s[4:5], exec
	s_cselect_b32 s13, s79, s9
	s_cselect_b32 s37, s78, s8
	s_add_u32 s38, s8, 0x100
	s_addc_u32 s39, s9, 0
	s_add_u32 s8, s10, 0x40080
	v_mov_b32_e32 v0, 0
	s_addc_u32 s9, s11, 0
	s_mov_b32 s40, -2
	v_mov_b32_e32 v1, v0
	s_waitcnt lgkmcnt(0)
	v_mov_b32_e32 v2, v0
	v_mov_b32_e32 v3, v0
	v_mov_b32_e32 v4, v0
	v_mov_b32_e32 v5, v0
	v_mov_b32_e32 v6, v0
	v_mov_b32_e32 v7, v0
	v_mov_b32_e32 v16, v0
	v_mov_b32_e32 v17, v0
	v_mov_b32_e32 v18, v0
	v_mov_b32_e32 v19, v0
	v_mov_b32_e32 v20, v0
	v_mov_b32_e32 v21, v0
	v_mov_b32_e32 v22, v0
	v_mov_b32_e32 v23, v0
	v_mov_b32_e32 v32, v0
	v_mov_b32_e32 v33, v0
	v_mov_b32_e32 v34, v0
	v_mov_b32_e32 v35, v0
	v_mov_b32_e32 v36, v0
	v_mov_b32_e32 v37, v0
	v_mov_b32_e32 v38, v0
	v_mov_b32_e32 v39, v0
	v_mov_b32_e32 v48, v0
	v_mov_b32_e32 v49, v0
	v_mov_b32_e32 v50, v0
	v_mov_b32_e32 v51, v0
	v_mov_b32_e32 v52, v0
	v_mov_b32_e32 v53, v0
	v_mov_b32_e32 v54, v0
	v_mov_b32_e32 v55, v0
	v_mov_b32_e32 v8, v0
	v_mov_b32_e32 v9, v0
	v_mov_b32_e32 v10, v0
	v_mov_b32_e32 v11, v0
	v_mov_b32_e32 v12, v0
	v_mov_b32_e32 v13, v0
	v_mov_b32_e32 v14, v0
	v_mov_b32_e32 v15, v0
	v_mov_b32_e32 v24, v0
	v_mov_b32_e32 v25, v0
	v_mov_b32_e32 v26, v0
	v_mov_b32_e32 v27, v0
	v_mov_b32_e32 v28, v0
	v_mov_b32_e32 v29, v0
	v_mov_b32_e32 v30, v0
	v_mov_b32_e32 v31, v0
	v_mov_b32_e32 v40, v0
	v_mov_b32_e32 v41, v0
	v_mov_b32_e32 v42, v0
	v_mov_b32_e32 v43, v0
	v_mov_b32_e32 v44, v0
	v_mov_b32_e32 v45, v0
	v_mov_b32_e32 v46, v0
	v_mov_b32_e32 v47, v0
	v_mov_b32_e32 v56, v0
	v_mov_b32_e32 v57, v0
	v_mov_b32_e32 v58, v0
	v_mov_b32_e32 v59, v0
	v_mov_b32_e32 v60, v0
	v_mov_b32_e32 v61, v0
	v_mov_b32_e32 v62, v0
	v_mov_b32_e32 v63, v0
	v_mov_b32_e32 v64, v0
	v_mov_b32_e32 v65, v0
	v_mov_b32_e32 v66, v0
	v_mov_b32_e32 v67, v0
	v_mov_b32_e32 v68, v0
	v_mov_b32_e32 v69, v0
	v_mov_b32_e32 v70, v0
	v_mov_b32_e32 v71, v0
	v_mov_b32_e32 v80, v0
	v_mov_b32_e32 v81, v0
	v_mov_b32_e32 v82, v0
	v_mov_b32_e32 v83, v0
	v_mov_b32_e32 v84, v0
	v_mov_b32_e32 v85, v0
	v_mov_b32_e32 v86, v0
	v_mov_b32_e32 v87, v0
	v_mov_b32_e32 v96, v0
	v_mov_b32_e32 v97, v0
	v_mov_b32_e32 v98, v0
	v_mov_b32_e32 v99, v0
	v_mov_b32_e32 v100, v0
	v_mov_b32_e32 v101, v0
	v_mov_b32_e32 v102, v0
	v_mov_b32_e32 v103, v0
	v_mov_b32_e32 v112, v0
	v_mov_b32_e32 v113, v0
	v_mov_b32_e32 v114, v0
	v_mov_b32_e32 v115, v0
	v_mov_b32_e32 v116, v0
	v_mov_b32_e32 v117, v0
	v_mov_b32_e32 v118, v0
	v_mov_b32_e32 v119, v0
	v_mov_b32_e32 v72, v0
	v_mov_b32_e32 v73, v0
	v_mov_b32_e32 v74, v0
	v_mov_b32_e32 v75, v0
	v_mov_b32_e32 v76, v0
	v_mov_b32_e32 v77, v0
	v_mov_b32_e32 v78, v0
	v_mov_b32_e32 v79, v0
	v_mov_b32_e32 v88, v0
	v_mov_b32_e32 v89, v0
	v_mov_b32_e32 v90, v0
	v_mov_b32_e32 v91, v0
	v_mov_b32_e32 v92, v0
	v_mov_b32_e32 v93, v0
	v_mov_b32_e32 v94, v0
	v_mov_b32_e32 v95, v0
	v_mov_b32_e32 v104, v0
	v_mov_b32_e32 v105, v0
	v_mov_b32_e32 v106, v0
	v_mov_b32_e32 v107, v0
	v_mov_b32_e32 v108, v0
	v_mov_b32_e32 v109, v0
	v_mov_b32_e32 v110, v0
	v_mov_b32_e32 v111, v0
	v_mov_b32_e32 v120, v0
	v_mov_b32_e32 v121, v0
	v_mov_b32_e32 v122, v0
	v_mov_b32_e32 v123, v0
	v_mov_b32_e32 v124, v0
	v_mov_b32_e32 v125, v0
	v_mov_b32_e32 v126, v0
	v_mov_b32_e32 v127, v0
	.p2align 6

;     __device__ bool next(int i, Unit& u) const { Unit b; if (!base.next(i / 3, b)) return false; u.pm = b.pm; u.pn = b.pn + 4 * (i % 3); return true; }
;     __device__ bool next(int i, Unit& u) const { Unit b; if (!base.next(i / 3, b)) return false; const int br = i % 3; u.pm = b.pm + 64 * br; u.pn = b.pn + 4 * br; return true; }
; template <class Epi, class Sched, bool ALIGN_EPI = false, bool SP2 = false>
; __device__ __forceinline__ void gemm_phase(PG8_LAS unsigned char* lds, const Gemm g, const Sched& S, const Epi& E) {
;     ...
;     for (;;) {
;         const bool has_next = S.next(ui + 1, nxt);
;         const char* nA = has_next ? (const char*)g.A + (size_t)nxt.pm * tstep : cA; const char* nB = has_next ? (const char*)g.Bt + (size_t)nxt.pn * tstep : cB;
;         for (int t = 0; t < nt; t += 2) {
;             const bool last = (t == nt - 2);
;             const char* a1 = cA + (size_t)(t + 1) * kstep;
;             const char* a2 = last ? nA : cA + (size_t)(t + 2) * kstep; const char* b2 = last ? nB : cB + (size_t)(t + 2) * kstep;
;             const char* a3 = a2 + kstep; const char* b3 = b2 + kstep;
;     ...
; #pragma unroll
;         for (int a = 0; a < 2; ++a)
; #pragma unroll
;             for (int b = 0; b < 2; ++b)
; #pragma unroll
;                 for (int m = 0; m < 4; ++m)
; #pragma unroll
;                     for (int n = 0; n < 2; ++n) acc[a][b][m][n] = (f32x4){0.f, 0.f, 0.f, 0.f};
;         cur = nxt; cA = nA; cB = nB; ++ui;
.LBB0_1200:
	v_mov_b32_e32 v123, 0
	s_andn2_b64 vcc, exec, s[24:25]
	v_mov_b32_e32 v122, v123
	v_mov_b32_e32 v121, v123
	v_mov_b32_e32 v120, v123
	v_mov_b32_e32 v127, v123
	v_mov_b32_e32 v126, v123
	v_mov_b32_e32 v125, v123
	v_mov_b32_e32 v124, v123
	v_mov_b32_e32 v111, v123
	v_mov_b32_e32 v110, v123
	v_mov_b32_e32 v109, v123
	v_mov_b32_e32 v108, v123
	v_mov_b32_e32 v107, v123
	v_mov_b32_e32 v106, v123
	v_mov_b32_e32 v105, v123
	v_mov_b32_e32 v104, v123
	v_mov_b32_e32 v95, v123
	v_mov_b32_e32 v94, v123
	v_mov_b32_e32 v93, v123
	v_mov_b32_e32 v92, v123
	v_mov_b32_e32 v91, v123
	v_mov_b32_e32 v90, v123
	v_mov_b32_e32 v89, v123
	v_mov_b32_e32 v88, v123
	v_mov_b32_e32 v79, v123
	v_mov_b32_e32 v78, v123
	v_mov_b32_e32 v77, v123
	v_mov_b32_e32 v76, v123
	v_mov_b32_e32 v75, v123
	v_mov_b32_e32 v74, v123
	v_mov_b32_e32 v73, v123
	v_mov_b32_e32 v72, v123
	v_mov_b32_e32 v119, v123
	v_mov_b32_e32 v118, v123
	v_mov_b32_e32 v117, v123
	v_mov_b32_e32 v116, v123
	v_mov_b32_e32 v115, v123
	v_mov_b32_e32 v114, v123
	v_mov_b32_e32 v113, v123
	v_mov_b32_e32 v112, v123
	v_mov_b32_e32 v103, v123
	v_mov_b32_e32 v102, v123
	v_mov_b32_e32 v101, v123
	v_mov_b32_e32 v100, v123
	v_mov_b32_e32 v99, v123
	v_mov_b32_e32 v98, v123
	v_mov_b32_e32 v97, v123
	v_mov_b32_e32 v96, v123
	v_mov_b32_e32 v87, v123
	v_mov_b32_e32 v86, v123
	v_mov_b32_e32 v85, v123
	v_mov_b32_e32 v84, v123
	v_mov_b32_e32 v83, v123
	v_mov_b32_e32 v82, v123
	v_mov_b32_e32 v81, v123
	v_mov_b32_e32 v80, v123
	v_mov_b32_e32 v71, v123
	v_mov_b32_e32 v70, v123
	v_mov_b32_e32 v69, v123
	v_mov_b32_e32 v68, v123
	v_mov_b32_e32 v67, v123
	v_mov_b32_e32 v66, v123
	v_mov_b32_e32 v65, v123
	v_mov_b32_e32 v64, v123
	v_mov_b32_e32 v63, v123
	v_mov_b32_e32 v62, v123
	v_mov_b32_e32 v61, v123
	v_mov_b32_e32 v60, v123
	v_mov_b32_e32 v59, v123
	v_mov_b32_e32 v58, v123
	v_mov_b32_e32 v57, v123
	v_mov_b32_e32 v56, v123
	v_mov_b32_e32 v47, v123
	v_mov_b32_e32 v46, v123
	v_mov_b32_e32 v45, v123
	v_mov_b32_e32 v44, v123
	v_mov_b32_e32 v43, v123
	v_mov_b32_e32 v42, v123
	v_mov_b32_e32 v41, v123
	v_mov_b32_e32 v40, v123
	v_mov_b32_e32 v31, v123
	v_mov_b32_e32 v30, v123
	v_mov_b32_e32 v29, v123
	v_mov_b32_e32 v28, v123
	v_mov_b32_e32 v27, v123
	v_mov_b32_e32 v26, v123
	v_mov_b32_e32 v25, v123
	v_mov_b32_e32 v24, v123
	v_mov_b32_e32 v15, v123
	v_mov_b32_e32 v14, v123
	v_mov_b32_e32 v13, v123
	v_mov_b32_e32 v12, v123
	v_mov_b32_e32 v11, v123
	v_mov_b32_e32 v10, v123
	v_mov_b32_e32 v9, v123
	v_mov_b32_e32 v8, v123
	v_mov_b32_e32 v55, v123
	v_mov_b32_e32 v54, v123
	v_mov_b32_e32 v53, v123
	v_mov_b32_e32 v52, v123
	v_mov_b32_e32 v51, v123
	v_mov_b32_e32 v50, v123
	v_mov_b32_e32 v49, v123
	v_mov_b32_e32 v48, v123
	v_mov_b32_e32 v39, v123
	v_mov_b32_e32 v38, v123
	v_mov_b32_e32 v37, v123
	v_mov_b32_e32 v36, v123
	v_mov_b32_e32 v35, v123
	v_mov_b32_e32 v34, v123
	v_mov_b32_e32 v33, v123
	v_mov_b32_e32 v32, v123
	v_mov_b32_e32 v23, v123
	v_mov_b32_e32 v22, v123
	v_mov_b32_e32 v21, v123
	v_mov_b32_e32 v20, v123
	v_mov_b32_e32 v19, v123
	v_mov_b32_e32 v18, v123
	v_mov_b32_e32 v17, v123
	v_mov_b32_e32 v16, v123
	v_mov_b32_e32 v7, v123
	v_mov_b32_e32 v6, v123
	v_mov_b32_e32 v5, v123
	v_mov_b32_e32 v4, v123
	v_mov_b32_e32 v3, v123
	v_mov_b32_e32 v2, v123
	v_mov_b32_e32 v1, v123
	v_mov_b32_e32 v0, v123
	s_cbranch_vccnz .LBB0_1203
	s_add_u32 s70, s42, 0x100
	s_addc_u32 s71, s43, 0
	s_add_u32 s42, s46, 0x80
	v_mov_b32_e32 v0, 0
	s_addc_u32 s43, s47, 0
	s_mov_b32 s46, 0
	v_mov_b32_e32 v1, v0
	v_mov_b32_e32 v2, v0
	v_mov_b32_e32 v3, v0
	v_mov_b32_e32 v4, v0
	v_mov_b32_e32 v5, v0
	v_mov_b32_e32 v6, v0
	v_mov_b32_e32 v7, v0
	v_mov_b32_e32 v16, v0
	v_mov_b32_e32 v17, v0
	v_mov_b32_e32 v18, v0
	v_mov_b32_e32 v19, v0
	v_mov_b32_e32 v20, v0
	v_mov_b32_e32 v21, v0
	v_mov_b32_e32 v22, v0
	v_mov_b32_e32 v23, v0
	v_mov_b32_e32 v32, v0
	v_mov_b32_e32 v33, v0
	v_mov_b32_e32 v34, v0
	v_mov_b32_e32 v35, v0
	v_mov_b32_e32 v36, v0
	v_mov_b32_e32 v37, v0
	v_mov_b32_e32 v38, v0
	v_mov_b32_e32 v39, v0
	v_mov_b32_e32 v48, v0
	v_mov_b32_e32 v49, v0
	v_mov_b32_e32 v50, v0
	v_mov_b32_e32 v51, v0
	v_mov_b32_e32 v52, v0
	v_mov_b32_e32 v53, v0
	v_mov_b32_e32 v54, v0
	v_mov_b32_e32 v55, v0
	v_mov_b32_e32 v8, v0
	v_mov_b32_e32 v9, v0
	v_mov_b32_e32 v10, v0
	v_mov_b32_e32 v11, v0
	v_mov_b32_e32 v12, v0
	v_mov_b32_e32 v13, v0
	v_mov_b32_e32 v14, v0
	v_mov_b32_e32 v15, v0
	v_mov_b32_e32 v24, v0
	v_mov_b32_e32 v25, v0
	v_mov_b32_e32 v26, v0
	v_mov_b32_e32 v27, v0
	v_mov_b32_e32 v28, v0
	v_mov_b32_e32 v29, v0
	v_mov_b32_e32 v30, v0
	v_mov_b32_e32 v31, v0
	v_mov_b32_e32 v40, v0
	v_mov_b32_e32 v41, v0
	v_mov_b32_e32 v42, v0
	v_mov_b32_e32 v43, v0
	v_mov_b32_e32 v44, v0
	v_mov_b32_e32 v45, v0
	v_mov_b32_e32 v46, v0
	v_mov_b32_e32 v47, v0
	v_mov_b32_e32 v56, v0
	v_mov_b32_e32 v57, v0
	v_mov_b32_e32 v58, v0
	v_mov_b32_e32 v59, v0
	v_mov_b32_e32 v60, v0
	v_mov_b32_e32 v61, v0
	v_mov_b32_e32 v62, v0
	v_mov_b32_e32 v63, v0
	v_mov_b32_e32 v64, v0
	v_mov_b32_e32 v65, v0
	v_mov_b32_e32 v66, v0
	v_mov_b32_e32 v67, v0
	v_mov_b32_e32 v68, v0
	v_mov_b32_e32 v69, v0
	v_mov_b32_e32 v70, v0
	v_mov_b32_e32 v71, v0
	v_mov_b32_e32 v80, v0
	v_mov_b32_e32 v81, v0
	v_mov_b32_e32 v82, v0
	v_mov_b32_e32 v83, v0
	v_mov_b32_e32 v84, v0
	v_mov_b32_e32 v85, v0
	v_mov_b32_e32 v86, v0
	v_mov_b32_e32 v87, v0
	v_mov_b32_e32 v96, v0
	v_mov_b32_e32 v97, v0
	v_mov_b32_e32 v98, v0
	v_mov_b32_e32 v99, v0
	v_mov_b32_e32 v100, v0
	v_mov_b32_e32 v101, v0
	v_mov_b32_e32 v102, v0
	v_mov_b32_e32 v103, v0
	v_mov_b32_e32 v112, v0
	v_mov_b32_e32 v113, v0
	v_mov_b32_e32 v114, v0
	v_mov_b32_e32 v115, v0
	v_mov_b32_e32 v116, v0
	v_mov_b32_e32 v117, v0
	v_mov_b32_e32 v118, v0
	v_mov_b32_e32 v119, v0
	v_mov_b32_e32 v72, v0
	v_mov_b32_e32 v73, v0
	v_mov_b32_e32 v74, v0
	v_mov_b32_e32 v75, v0
	v_mov_b32_e32 v76, v0
	v_mov_b32_e32 v77, v0
	v_mov_b32_e32 v78, v0
	v_mov_b32_e32 v79, v0
	v_mov_b32_e32 v88, v0
	v_mov_b32_e32 v89, v0
	v_mov_b32_e32 v90, v0
	v_mov_b32_e32 v91, v0
	v_mov_b32_e32 v92, v0
	v_mov_b32_e32 v93, v0
	v_mov_b32_e32 v94, v0
	v_mov_b32_e32 v95, v0
	v_mov_b32_e32 v104, v0
	v_mov_b32_e32 v105, v0
	v_mov_b32_e32 v106, v0
	v_mov_b32_e32 v107, v0
	v_mov_b32_e32 v108, v0
	v_mov_b32_e32 v109, v0
	v_mov_b32_e32 v110, v0
	v_mov_b32_e32 v111, v0
	v_mov_b32_e32 v124, v0
	v_mov_b32_e32 v125, v0
	v_mov_b32_e32 v126, v0
	v_mov_b32_e32 v127, v0
	v_mov_b32_e32 v120, v0
	v_mov_b32_e32 v121, v0
	v_mov_b32_e32 v122, v0
	v_mov_b32_e32 v123, v0
	.p2align 6

;     __device__ bool next(int i, Unit& u) const { Unit b; if (!base.next(i / 3, b)) return false; u.pm = b.pm; u.pn = b.pn + 4 * (i % 3); return true; }
;     __device__ bool next(int i, Unit& u) const { Unit b; if (!base.next(i / 3, b)) return false; const int br = i % 3; u.pm = b.pm + 64 * br; u.pn = b.pn + 4 * br; return true; }
; template <class Epi, class Sched, bool ALIGN_EPI = false, bool SP2 = false>
; __device__ __forceinline__ void gemm_phase(PG8_LAS unsigned char* lds, const Gemm g, const Sched& S, const Epi& E) {
;     ...
;     for (;;) {
;         const bool has_next = S.next(ui + 1, nxt);
;         const char* nA = has_next ? (const char*)g.A + (size_t)nxt.pm * tstep : cA; const char* nB = has_next ? (const char*)g.Bt + (size_t)nxt.pn * tstep : cB;
;         for (int t = 0; t < nt; t += 2) {
;             const bool last = (t == nt - 2);
;             const char* a1 = cA + (size_t)(t + 1) * kstep;
;             const char* a2 = last ? nA : cA + (size_t)(t + 2) * kstep; const char* b2 = last ? nB : cB + (size_t)(t + 2) * kstep;
;             const char* a3 = a2 + kstep; const char* b3 = b2 + kstep;
;     ...
; #pragma unroll
;         for (int a = 0; a < 2; ++a)
; #pragma unroll
;             for (int b = 0; b < 2; ++b)
; #pragma unroll
;                 for (int m = 0; m < 4; ++m)
; #pragma unroll
;                     for (int n = 0; n < 2; ++n) acc[a][b][m][n] = (f32x4){0.f, 0.f, 0.f, 0.f};
;         cur = nxt; cA = nA; cB = nB; ++ui;
.LBB0_1227:
	v_mov_b32_e32 v123, 0
	s_andn2_b64 vcc, exec, s[26:27]
	v_mov_b32_e32 v122, v123
	v_mov_b32_e32 v121, v123
	v_mov_b32_e32 v120, v123
	v_mov_b32_e32 v127, v123
	v_mov_b32_e32 v126, v123
	v_mov_b32_e32 v125, v123
	v_mov_b32_e32 v124, v123
	v_mov_b32_e32 v111, v123
	v_mov_b32_e32 v110, v123
	v_mov_b32_e32 v109, v123
	v_mov_b32_e32 v108, v123
	v_mov_b32_e32 v107, v123
	v_mov_b32_e32 v106, v123
	v_mov_b32_e32 v105, v123
	v_mov_b32_e32 v104, v123
	v_mov_b32_e32 v95, v123
	v_mov_b32_e32 v94, v123
	v_mov_b32_e32 v93, v123
	v_mov_b32_e32 v92, v123
	v_mov_b32_e32 v91, v123
	v_mov_b32_e32 v90, v123
	v_mov_b32_e32 v89, v123
	v_mov_b32_e32 v88, v123
	v_mov_b32_e32 v79, v123
	v_mov_b32_e32 v78, v123
	v_mov_b32_e32 v77, v123
	v_mov_b32_e32 v76, v123
	v_mov_b32_e32 v75, v123
	v_mov_b32_e32 v74, v123
	v_mov_b32_e32 v73, v123
	v_mov_b32_e32 v72, v123
	v_mov_b32_e32 v119, v123
	v_mov_b32_e32 v118, v123
	v_mov_b32_e32 v117, v123
	v_mov_b32_e32 v116, v123
	v_mov_b32_e32 v115, v123
	v_mov_b32_e32 v114, v123
	v_mov_b32_e32 v113, v123
	v_mov_b32_e32 v112, v123
	v_mov_b32_e32 v103, v123
	v_mov_b32_e32 v102, v123
	v_mov_b32_e32 v101, v123
	v_mov_b32_e32 v100, v123
	v_mov_b32_e32 v99, v123
	v_mov_b32_e32 v98, v123
	v_mov_b32_e32 v97, v123
	v_mov_b32_e32 v96, v123
	v_mov_b32_e32 v87, v123
	v_mov_b32_e32 v86, v123
	v_mov_b32_e32 v85, v123
	v_mov_b32_e32 v84, v123
	v_mov_b32_e32 v83, v123
	v_mov_b32_e32 v82, v123
	v_mov_b32_e32 v81, v123
	v_mov_b32_e32 v80, v123
	v_mov_b32_e32 v71, v123
	v_mov_b32_e32 v70, v123
	v_mov_b32_e32 v69, v123
	v_mov_b32_e32 v68, v123
	v_mov_b32_e32 v67, v123
	v_mov_b32_e32 v66, v123
	v_mov_b32_e32 v65, v123
	v_mov_b32_e32 v64, v123
	v_mov_b32_e32 v63, v123
	v_mov_b32_e32 v62, v123
	v_mov_b32_e32 v61, v123
	v_mov_b32_e32 v60, v123
	v_mov_b32_e32 v59, v123
	v_mov_b32_e32 v58, v123
	v_mov_b32_e32 v57, v123
	v_mov_b32_e32 v56, v123
	v_mov_b32_e32 v47, v123
	v_mov_b32_e32 v46, v123
	v_mov_b32_e32 v45, v123
	v_mov_b32_e32 v44, v123
	v_mov_b32_e32 v43, v123
	v_mov_b32_e32 v42, v123
	v_mov_b32_e32 v41, v123
	v_mov_b32_e32 v40, v123
	v_mov_b32_e32 v31, v123
	v_mov_b32_e32 v30, v123
	v_mov_b32_e32 v29, v123
	v_mov_b32_e32 v28, v123
	v_mov_b32_e32 v27, v123
	v_mov_b32_e32 v26, v123
	v_mov_b32_e32 v25, v123
	v_mov_b32_e32 v24, v123
	v_mov_b32_e32 v15, v123
	v_mov_b32_e32 v14, v123
	v_mov_b32_e32 v13, v123
	v_mov_b32_e32 v12, v123
	v_mov_b32_e32 v11, v123
	v_mov_b32_e32 v10, v123
	v_mov_b32_e32 v9, v123
	v_mov_b32_e32 v8, v123
	v_mov_b32_e32 v55, v123
	v_mov_b32_e32 v54, v123
	v_mov_b32_e32 v53, v123
	v_mov_b32_e32 v52, v123
	v_mov_b32_e32 v51, v123
	v_mov_b32_e32 v50, v123
	v_mov_b32_e32 v49, v123
	v_mov_b32_e32 v48, v123
	v_mov_b32_e32 v39, v123
	v_mov_b32_e32 v38, v123
	v_mov_b32_e32 v37, v123
	v_mov_b32_e32 v36, v123
	v_mov_b32_e32 v35, v123
	v_mov_b32_e32 v34, v123
	v_mov_b32_e32 v33, v123
	v_mov_b32_e32 v32, v123
	v_mov_b32_e32 v23, v123
	v_mov_b32_e32 v22, v123
	v_mov_b32_e32 v21, v123
	v_mov_b32_e32 v20, v123
	v_mov_b32_e32 v19, v123
	v_mov_b32_e32 v18, v123
	v_mov_b32_e32 v17, v123
	v_mov_b32_e32 v16, v123
	v_mov_b32_e32 v7, v123
	v_mov_b32_e32 v6, v123
	v_mov_b32_e32 v5, v123
	v_mov_b32_e32 v4, v123
	v_mov_b32_e32 v3, v123
	v_mov_b32_e32 v2, v123
	v_mov_b32_e32 v1, v123
	v_mov_b32_e32 v0, v123
	s_cbranch_vccnz .LBB0_1231
	s_add_u32 s12, s50, 0x100
	s_addc_u32 s13, s51, 0
	s_add_u32 s4, s52, 0x80
	v_mov_b32_e32 v0, 0
	s_addc_u32 s5, s53, 0
	s_mov_b32 s50, 0
	v_mov_b32_e32 v1, v0
	v_mov_b32_e32 v2, v0
	v_mov_b32_e32 v3, v0
	v_mov_b32_e32 v4, v0
	v_mov_b32_e32 v5, v0
	v_mov_b32_e32 v6, v0
	v_mov_b32_e32 v7, v0
	v_mov_b32_e32 v16, v0
	v_mov_b32_e32 v17, v0
	v_mov_b32_e32 v18, v0
	v_mov_b32_e32 v19, v0
	v_mov_b32_e32 v20, v0
	v_mov_b32_e32 v21, v0
	v_mov_b32_e32 v22, v0
	v_mov_b32_e32 v23, v0
	v_mov_b32_e32 v32, v0
	v_mov_b32_e32 v33, v0
	v_mov_b32_e32 v34, v0
	v_mov_b32_e32 v35, v0
	v_mov_b32_e32 v36, v0
	v_mov_b32_e32 v37, v0
	v_mov_b32_e32 v38, v0
	v_mov_b32_e32 v39, v0
	v_mov_b32_e32 v48, v0
	v_mov_b32_e32 v49, v0
	v_mov_b32_e32 v50, v0
	v_mov_b32_e32 v51, v0
	v_mov_b32_e32 v52, v0
	v_mov_b32_e32 v53, v0
	v_mov_b32_e32 v54, v0
	v_mov_b32_e32 v55, v0
	v_mov_b32_e32 v8, v0
	v_mov_b32_e32 v9, v0
	v_mov_b32_e32 v10, v0
	v_mov_b32_e32 v11, v0
	v_mov_b32_e32 v12, v0
	v_mov_b32_e32 v13, v0
	v_mov_b32_e32 v14, v0
	v_mov_b32_e32 v15, v0
	v_mov_b32_e32 v24, v0
	v_mov_b32_e32 v25, v0
	v_mov_b32_e32 v26, v0
	v_mov_b32_e32 v27, v0
	v_mov_b32_e32 v28, v0
	v_mov_b32_e32 v29, v0
	v_mov_b32_e32 v30, v0
	v_mov_b32_e32 v31, v0
	v_mov_b32_e32 v40, v0
	v_mov_b32_e32 v41, v0
	v_mov_b32_e32 v42, v0
	v_mov_b32_e32 v43, v0
	v_mov_b32_e32 v44, v0
	v_mov_b32_e32 v45, v0
	v_mov_b32_e32 v46, v0
	v_mov_b32_e32 v47, v0
	v_mov_b32_e32 v56, v0
	v_mov_b32_e32 v57, v0
	v_mov_b32_e32 v58, v0
	v_mov_b32_e32 v59, v0
	v_mov_b32_e32 v60, v0
	v_mov_b32_e32 v61, v0
	v_mov_b32_e32 v62, v0
	v_mov_b32_e32 v63, v0
	v_mov_b32_e32 v64, v0
	v_mov_b32_e32 v65, v0
	v_mov_b32_e32 v66, v0
	v_mov_b32_e32 v67, v0
	v_mov_b32_e32 v68, v0
	v_mov_b32_e32 v69, v0
	v_mov_b32_e32 v70, v0
	v_mov_b32_e32 v71, v0
	v_mov_b32_e32 v80, v0
	v_mov_b32_e32 v81, v0
	v_mov_b32_e32 v82, v0
	v_mov_b32_e32 v83, v0
	v_mov_b32_e32 v84, v0
	v_mov_b32_e32 v85, v0
	v_mov_b32_e32 v86, v0
	v_mov_b32_e32 v87, v0
	v_mov_b32_e32 v96, v0
	v_mov_b32_e32 v97, v0
	v_mov_b32_e32 v98, v0
	v_mov_b32_e32 v99, v0
	v_mov_b32_e32 v100, v0
	v_mov_b32_e32 v101, v0
	v_mov_b32_e32 v102, v0
	v_mov_b32_e32 v103, v0
	v_mov_b32_e32 v112, v0
	v_mov_b32_e32 v113, v0
	v_mov_b32_e32 v114, v0
	v_mov_b32_e32 v115, v0
	v_mov_b32_e32 v116, v0
	v_mov_b32_e32 v117, v0
	v_mov_b32_e32 v118, v0
	v_mov_b32_e32 v119, v0
	v_mov_b32_e32 v72, v0
	v_mov_b32_e32 v73, v0
	v_mov_b32_e32 v74, v0
	v_mov_b32_e32 v75, v0
	v_mov_b32_e32 v76, v0
	v_mov_b32_e32 v77, v0
	v_mov_b32_e32 v78, v0
	v_mov_b32_e32 v79, v0
	v_mov_b32_e32 v88, v0
	v_mov_b32_e32 v89, v0
	v_mov_b32_e32 v90, v0
	v_mov_b32_e32 v91, v0
	v_mov_b32_e32 v92, v0
	v_mov_b32_e32 v93, v0
	v_mov_b32_e32 v94, v0
	v_mov_b32_e32 v95, v0
	v_mov_b32_e32 v104, v0
	v_mov_b32_e32 v105, v0
	v_mov_b32_e32 v106, v0
	v_mov_b32_e32 v107, v0
	v_mov_b32_e32 v108, v0
	v_mov_b32_e32 v109, v0
	v_mov_b32_e32 v110, v0
	v_mov_b32_e32 v111, v0
	v_mov_b32_e32 v124, v0
	v_mov_b32_e32 v125, v0
	v_mov_b32_e32 v126, v0
	v_mov_b32_e32 v127, v0
	v_mov_b32_e32 v120, v0
	v_mov_b32_e32 v121, v0
	v_mov_b32_e32 v122, v0
	v_mov_b32_e32 v123, v0
	.p2align 6

; DI float xhalf_sum(float m) { auto rr = __builtin_amdgcn_permlane32_swap(__float_as_uint(m), __float_as_uint(m), false, false); return __uint_as_float(rr[0]) + __uint_as_float(rr[1]); }
; template <int DQK, int DV, bool CAUSAL, int KT, bool PRIO>
; DI void attn_unit(const bf16_t* Qb, int qpitch, const bf16_t* Kb, int kpitch, const bf16_t* Vtb, int vpitch, bf16_t* Ob, int opitch, int q0, int nt, LAS unsigned char* lds, float kbound, const float* qgain, const int* qpos, float qscale) {
;     ...
;     f32x16 o[DV / 32], negm;
; #pragma unroll
;     for (int i = 0; i < 16; ++i) negm[i] = 0.f;
; #pragma unroll
;     for (int d = 0; d < DV / 32; ++d)
; #pragma unroll
;         for (int i = 0; i < 16; ++i) o[d][i] = 0.f;
;     float mrun = 0.f, lrun = 0.f; bool first = true;
;     bool nomax = false;
;     if (PRIO) {
;         float q2 = 0.f;
; #pragma unroll
;         for (int ks = 0; ks < DQK / 16; ++ks)
; #pragma unroll
;             for (int e = 0; e < 8; ++e) { const float v = __uint_as_float(((unsigned)(unsigned short)qf[ks][e]) << 16); q2 += v * v; }
;         q2 = xhalf_sum(q2);
;         nomax = __all(sqrtf(q2) * kbound <= 100.0f) != 0;
;     }
;     lstore(0);
;     __syncthreads();
.LBB0_1486:
	s_waitcnt vmcnt(0) lgkmcnt(0)
	v_and_b32_e32 v9, 0xffff0000, v116
	v_lshlrev_b32_e32 v8, 16, v116
	v_mul_f32_e32 v11, v9, v9
	v_fmac_f32_e32 v11, v8, v8
	v_lshlrev_b32_e32 v8, 16, v117
	v_fmac_f32_e32 v11, v8, v8
	v_and_b32_e32 v8, 0xffff0000, v117
	v_fmac_f32_e32 v11, v8, v8
	v_lshlrev_b32_e32 v8, 16, v118
	v_fmac_f32_e32 v11, v8, v8
	v_and_b32_e32 v8, 0xffff0000, v118
	v_fmac_f32_e32 v11, v8, v8
	v_lshlrev_b32_e32 v8, 16, v119
	v_fmac_f32_e32 v11, v8, v8
	v_and_b32_e32 v8, 0xffff0000, v119
	v_fmac_f32_e32 v11, v8, v8
	v_lshlrev_b32_e32 v8, 16, v120
	v_fmac_f32_e32 v11, v8, v8
	v_and_b32_e32 v8, 0xffff0000, v120
	v_fmac_f32_e32 v11, v8, v8
	v_lshlrev_b32_e32 v8, 16, v121
	v_fmac_f32_e32 v11, v8, v8
	v_and_b32_e32 v8, 0xffff0000, v121
	v_fmac_f32_e32 v11, v8, v8
	v_lshlrev_b32_e32 v8, 16, v122
	v_fmac_f32_e32 v11, v8, v8
	v_and_b32_e32 v8, 0xffff0000, v122
	v_fmac_f32_e32 v11, v8, v8
	v_lshlrev_b32_e32 v8, 16, v123
	v_fmac_f32_e32 v11, v8, v8
	v_and_b32_e32 v8, 0xffff0000, v123
	v_fmac_f32_e32 v11, v8, v8
	v_lshlrev_b32_e32 v8, 16, v124
	v_fmac_f32_e32 v11, v8, v8
	v_and_b32_e32 v8, 0xffff0000, v124
	v_fmac_f32_e32 v11, v8, v8
	v_lshlrev_b32_e32 v8, 16, v125
	v_fmac_f32_e32 v11, v8, v8
	v_and_b32_e32 v8, 0xffff0000, v125
	v_fmac_f32_e32 v11, v8, v8
	v_lshlrev_b32_e32 v8, 16, v126
	v_fmac_f32_e32 v11, v8, v8
	v_and_b32_e32 v8, 0xffff0000, v126
	v_fmac_f32_e32 v11, v8, v8
	v_lshlrev_b32_e32 v8, 16, v127
	v_fmac_f32_e32 v11, v8, v8
	v_and_b32_e32 v8, 0xffff0000, v127
	v_fmac_f32_e32 v11, v8, v8
	v_lshlrev_b32_e32 v8, 16, v128
	v_fmac_f32_e32 v11, v8, v8
	v_and_b32_e32 v8, 0xffff0000, v128
	v_fmac_f32_e32 v11, v8, v8
	v_lshlrev_b32_e32 v8, 16, v129
	v_fmac_f32_e32 v11, v8, v8
	v_and_b32_e32 v8, 0xffff0000, v129
	v_fmac_f32_e32 v11, v8, v8
	v_lshlrev_b32_e32 v8, 16, v130
	v_fmac_f32_e32 v11, v8, v8
	v_and_b32_e32 v8, 0xffff0000, v130
	v_fmac_f32_e32 v11, v8, v8
	v_lshlrev_b32_e32 v8, 16, v131
	v_fmac_f32_e32 v11, v8, v8
	v_and_b32_e32 v8, 0xffff0000, v131
	v_fmac_f32_e32 v11, v8, v8
	v_lshlrev_b32_e32 v8, 16, v132
	v_fmac_f32_e32 v11, v8, v8
	v_and_b32_e32 v8, 0xffff0000, v132
	v_fmac_f32_e32 v11, v8, v8
	v_lshlrev_b32_e32 v8, 16, v133
	v_fmac_f32_e32 v11, v8, v8
	v_and_b32_e32 v8, 0xffff0000, v133
	v_fmac_f32_e32 v11, v8, v8
	v_lshlrev_b32_e32 v8, 16, v134
	v_fmac_f32_e32 v11, v8, v8
	v_and_b32_e32 v8, 0xffff0000, v134
	v_fmac_f32_e32 v11, v8, v8
	v_lshlrev_b32_e32 v8, 16, v135
	v_fmac_f32_e32 v11, v8, v8
	v_and_b32_e32 v8, 0xffff0000, v135
	v_fmac_f32_e32 v11, v8, v8
	v_lshlrev_b32_e32 v8, 16, v136
	v_fmac_f32_e32 v11, v8, v8
	v_and_b32_e32 v8, 0xffff0000, v136
	v_fmac_f32_e32 v11, v8, v8
	v_and_b32_e32 v9, 0xffff0000, v137
	v_lshlrev_b32_e32 v8, 16, v137
	v_pk_mul_f32 v[8:9], v[8:9], v[8:9]
	s_xor_b64 s[34:35], s[2:3], -1
	v_add_f32_e32 v8, v8, v11
	v_add_f32_e32 v11, v9, v8
	v_and_b32_e32 v9, 0xffff0000, v138
	v_lshlrev_b32_e32 v8, 16, v138
	v_pk_mul_f32 v[8:9], v[8:9], v[8:9]
	v_mad_i64_i32 v[2:3], s[2:3], v149, s88, 0
	v_add_f32_e32 v8, v8, v11
	v_add_f32_e32 v11, v9, v8
	v_and_b32_e32 v9, 0xffff0000, v139
	v_lshlrev_b32_e32 v8, 16, v139
	v_pk_mul_f32 v[8:9], v[8:9], v[8:9]
	v_mad_i64_i32 v[4:5], s[2:3], v151, s88, 0
	v_add_f32_e32 v8, v8, v11
	v_add_f32_e32 v8, v9, v8
	v_mov_b32_e32 v9, v8
	s_nop 1
	v_permlane32_swap_b32_e32 v8, v9
	v_add_f32_e32 v8, v8, v9
	v_mul_f32_e32 v9, 0x4f800000, v8
	v_cmp_gt_f32_e32 vcc, s91, v8
	v_mad_i64_i32 v[6:7], s[2:3], v153, s88, 0
	s_nop 0
	v_cndmask_b32_e32 v8, v8, v9, vcc
	v_sqrt_f32_e32 v9, v8
	s_add_i32 s2, s38, 0x100
	s_lshr_b32 s68, s2, 7
	v_mul_lo_u32 v178, v149, s53
	v_add_u32_e32 v11, -1, v9
	v_fma_f32 v12, -v11, v9, v8
	v_cmp_ge_f32_e64 s[2:3], 0, v12
	v_add_u32_e32 v12, 1, v9
	v_lshlrev_b32_e32 v179, 4, v150
	v_cndmask_b32_e64 v11, v9, v11, s[2:3]
	v_fma_f32 v9, -v12, v9, v8
	v_cmp_lt_f32_e64 s[2:3], 0, v9
	v_mul_lo_u32 v181, v151, s53
	v_lshlrev_b32_e32 v182, 4, v152
	v_cndmask_b32_e64 v9, v11, v12, s[2:3]
	v_mul_f32_e32 v11, 0x37800000, v9
	v_cndmask_b32_e32 v9, v9, v11, vcc
	v_cmp_class_f32_e32 vcc, v8, v176
	v_mul_lo_u32 v183, v153, s53
	v_lshlrev_b32_e32 v184, 4, v154
	v_cndmask_b32_e32 v8, v9, v8, vcc
	v_mul_f32_e32 v8, v174, v8
	v_cmp_ge_f32_e32 vcc, s52, v8
	v_add3_u32 v8, 0, v178, v179
	ds_write_b128 v8, v[96:99]
	v_add3_u32 v8, 0, v181, v182
	ds_write_b128 v8, v[100:103]
	v_add3_u32 v8, 0, v183, v184
	v_mul_lo_u32 v185, v68, s56
	ds_write_b128 v8, v[104:107]
	v_add_u32_e32 v8, 0, v185
	v_and_b32_e32 v186, 1, v69
	v_lshlrev_b32_e32 v186, 3, v186
	v_sub_u32_e32 v186, 0, v186
	v_lshl_add_u32 v186, v69, 4, v186
	v_add3_u32 v8, v8, v186, s57
	v_mul_lo_u32 v187, v74, s56
	ds_write2_b64 v8, v[108:109], v[110:111] offset1:2
	v_add_u32_e32 v8, 0, v187
	v_and_b32_e32 v188, 1, v75
	v_lshlrev_b32_e32 v188, 3, v188
	v_sub_u32_e32 v188, 0, v188
	v_lshl_add_u32 v188, v75, 4, v188
	v_and_b32_e32 v10, 31, v155
	v_add3_u32 v8, v8, v188, s57
	s_ashr_i32 s27, s26, 31
	s_and_b32 s69, s39, 0xffffffe0
	ds_write2_b64 v8, v[112:113], v[114:115] offset1:2
	v_mul_u32_u24_e32 v8, 0x110, v10
	s_cmp_lg_u64 vcc, exec
	v_add3_u32 v191, v0, v8, v0
	v_lshl_add_u64 v[8:9], s[22:23], 0, v[70:71]
	s_cselect_b64 s[2:3], -1, 0
	s_add_i32 s69, s69, s38
	v_lshl_add_u64 v[164:165], v[72:73], 1, v[8:9]
	v_lshl_add_u64 v[8:9], s[22:23], 0, v[64:65]
	v_lshl_add_u64 v[6:7], s[24:25], 0, v[6:7]
	v_lshl_add_u64 v[4:5], s[24:25], 0, v[4:5]
	v_lshl_add_u64 v[2:3], s[24:25], 0, v[2:3]
	v_mov_b32_e32 v14, v1
	v_mov_b32_e32 v15, v1
	v_or_b32_e32 v189, s69, v10
	v_mul_u32_u24_e32 v192, 0xd0, v10
	v_lshl_add_u64 v[166:167], v[66:67], 1, v[8:9]
	v_lshl_add_u64 v[168:169], v[62:63], 1, v[6:7]
	v_lshl_add_u64 v[170:171], v[60:61], 1, v[4:5]
	v_lshl_add_u64 v[172:173], v[58:59], 1, v[2:3]
	v_mov_b32_e32 v0, v1
	v_mov_b32_e32 v2, v1
	v_mov_b32_e32 v3, v1
	v_mov_b32_e32 v4, v1
	v_mov_b32_e32 v5, v1
	v_mov_b32_e32 v6, v1
	v_mov_b32_e32 v7, v1
	v_mov_b32_e32 v8, v1
	v_mov_b32_e32 v9, v1
	v_mov_b32_e32 v10, v1
	v_mov_b32_e32 v11, v1
	v_mov_b32_e32 v12, v1
	v_mov_b32_e32 v13, v1
	v_mov_b64_e32 v[30:31], v[14:15]
	v_mov_b64_e32 v[46:47], v[14:15]
	v_mov_b64_e32 v[62:63], v[14:15]
	s_mov_b32 s12, 0
	s_or_b32 s70, s69, 31
	v_lshl_add_u32 v190, v148, 4, 0
	v_lshlrev_b32_e32 v180, 2, v148
	s_mov_b64 s[40:41], -1
	v_mov_b32_e32 v193, 0
	s_mov_b32 s71, 63
	v_mov_b64_e32 v[28:29], v[12:13]
	v_mov_b64_e32 v[26:27], v[10:11]
	v_mov_b64_e32 v[24:25], v[8:9]
	v_mov_b64_e32 v[22:23], v[6:7]
	v_mov_b64_e32 v[20:21], v[4:5]
	v_mov_b64_e32 v[18:19], v[2:3]
	v_mov_b64_e32 v[16:17], v[0:1]
	v_mov_b64_e32 v[44:45], v[12:13]
	v_mov_b64_e32 v[42:43], v[10:11]
	v_mov_b64_e32 v[40:41], v[8:9]
	v_mov_b64_e32 v[38:39], v[6:7]
	v_mov_b64_e32 v[36:37], v[4:5]
	v_mov_b64_e32 v[34:35], v[2:3]
	v_mov_b64_e32 v[32:33], v[0:1]
	v_mov_b64_e32 v[60:61], v[12:13]
	v_mov_b64_e32 v[58:59], v[10:11]
	v_mov_b64_e32 v[56:57], v[8:9]
	v_mov_b64_e32 v[54:55], v[6:7]
	v_mov_b64_e32 v[52:53], v[4:5]
	v_mov_b64_e32 v[50:51], v[2:3]
	v_mov_b64_e32 v[48:49], v[0:1]
	v_mov_b32_e32 v0, 0
	s_waitcnt lgkmcnt(0)
	s_barrier
	.p2align 6

;     __device__ bool next(int i, Unit& u) const { Unit b; if (!base.next(i / 3, b)) return false; u.pm = b.pm; u.pn = b.pn + 4 * (i % 3); return true; }
;     __device__ bool next(int i, Unit& u) const { Unit b; if (!base.next(i / 3, b)) return false; const int br = i % 3; u.pm = b.pm + 64 * br; u.pn = b.pn + 4 * br; return true; }
; template <class Epi, class Sched, bool ALIGN_EPI = false, bool SP2 = false>
; __device__ __forceinline__ void gemm_phase(PG8_LAS unsigned char* lds, const Gemm g, const Sched& S, const Epi& E) {
;     ...
;         const bool has_next = S.next(ui + 1, nxt);
;         const char* nA = has_next ? (const char*)g.A + (size_t)nxt.pm * tstep : cA; const char* nB = has_next ? (const char*)g.Bt + (size_t)nxt.pn * tstep : cB;
;         for (int t = 0; t < nt; t += 2) {
;             const bool last = (t == nt - 2);
;             const char* a1 = cA + (size_t)(t + 1) * kstep;
;             const char* a2 = last ? nA : cA + (size_t)(t + 2) * kstep; const char* b2 = last ? nB : cB + (size_t)(t + 2) * kstep;
;             const char* a3 = a2 + kstep; const char* b3 = b2 + kstep;
;     ...
; #pragma unroll
;         for (int a = 0; a < 2; ++a)
; #pragma unroll
;             for (int b = 0; b < 2; ++b)
; #pragma unroll
;                 for (int m = 0; m < 4; ++m)
; #pragma unroll
;                     for (int n = 0; n < 2; ++n) acc[a][b][m][n] = (f32x4){0.f, 0.f, 0.f, 0.f};
;         cur = nxt; cA = nA; cB = nB; ++ui;
.LBB0_1598:
	s_ashr_i32 s21, s20, 31
	s_lshl_b64 s[12:13], s[20:21], 19
	s_add_u32 s24, s33, s12
	s_addc_u32 s25, s36, s13
	s_and_b64 s[12:13], s[2:3], exec
	s_cselect_b32 s12, s25, s41
	s_cselect_b32 s13, s24, s40
	s_ashr_i32 s23, s22, 31
	s_lshl_b64 s[26:27], s[22:23], 19
	s_add_u32 s26, s37, s26
	s_addc_u32 s27, s74, s27
	s_and_b64 s[42:43], s[2:3], exec
	s_cselect_b32 s21, s27, s39
	s_cselect_b32 s23, s26, s38
	s_add_u32 s62, s38, 0x100
	s_addc_u32 s63, s39, 0
	s_add_u32 s38, s40, 0x40080
	v_mov_b32_e32 v0, 0
	s_addc_u32 s39, s41, 0
	s_mov_b32 s64, -2
	v_mov_b32_e32 v1, v0
	v_mov_b32_e32 v2, v0
	v_mov_b32_e32 v3, v0
	v_mov_b32_e32 v4, v0
	v_mov_b32_e32 v5, v0
	v_mov_b32_e32 v6, v0
	v_mov_b32_e32 v7, v0
	v_mov_b32_e32 v16, v0
	v_mov_b32_e32 v17, v0
	v_mov_b32_e32 v18, v0
	v_mov_b32_e32 v19, v0
	v_mov_b32_e32 v20, v0
	v_mov_b32_e32 v21, v0
	v_mov_b32_e32 v22, v0
	v_mov_b32_e32 v23, v0
	v_mov_b32_e32 v32, v0
	v_mov_b32_e32 v33, v0
	v_mov_b32_e32 v34, v0
	v_mov_b32_e32 v35, v0
	v_mov_b32_e32 v36, v0
	v_mov_b32_e32 v37, v0
	v_mov_b32_e32 v38, v0
	v_mov_b32_e32 v39, v0
	v_mov_b32_e32 v48, v0
	v_mov_b32_e32 v49, v0
	v_mov_b32_e32 v50, v0
	v_mov_b32_e32 v51, v0
	v_mov_b32_e32 v52, v0
	v_mov_b32_e32 v53, v0
	v_mov_b32_e32 v54, v0
	v_mov_b32_e32 v55, v0
	v_mov_b32_e32 v8, v0
	v_mov_b32_e32 v9, v0
	v_mov_b32_e32 v10, v0
	v_mov_b32_e32 v11, v0
	v_mov_b32_e32 v12, v0
	v_mov_b32_e32 v13, v0
	v_mov_b32_e32 v14, v0
	v_mov_b32_e32 v15, v0
	v_mov_b32_e32 v24, v0
	v_mov_b32_e32 v25, v0
	v_mov_b32_e32 v26, v0
	v_mov_b32_e32 v27, v0
	v_mov_b32_e32 v28, v0
	v_mov_b32_e32 v29, v0
	v_mov_b32_e32 v30, v0
	v_mov_b32_e32 v31, v0
	v_mov_b32_e32 v40, v0
	v_mov_b32_e32 v41, v0
	v_mov_b32_e32 v42, v0
	v_mov_b32_e32 v43, v0
	v_mov_b32_e32 v44, v0
	v_mov_b32_e32 v45, v0
	v_mov_b32_e32 v46, v0
	v_mov_b32_e32 v47, v0
	v_mov_b32_e32 v56, v0
	v_mov_b32_e32 v57, v0
	v_mov_b32_e32 v58, v0
	v_mov_b32_e32 v59, v0
	v_mov_b32_e32 v60, v0
	v_mov_b32_e32 v61, v0
	v_mov_b32_e32 v62, v0
	v_mov_b32_e32 v63, v0
	v_mov_b32_e32 v64, v0
	v_mov_b32_e32 v65, v0
	v_mov_b32_e32 v66, v0
	v_mov_b32_e32 v67, v0
	v_mov_b32_e32 v68, v0
	v_mov_b32_e32 v69, v0
	v_mov_b32_e32 v70, v0
	v_mov_b32_e32 v71, v0
	v_mov_b32_e32 v96, v0
	v_mov_b32_e32 v97, v0
	v_mov_b32_e32 v98, v0
	v_mov_b32_e32 v99, v0
	v_mov_b32_e32 v100, v0
	v_mov_b32_e32 v101, v0
	v_mov_b32_e32 v102, v0
	v_mov_b32_e32 v103, v0
	v_mov_b32_e32 v112, v0
	v_mov_b32_e32 v113, v0
	v_mov_b32_e32 v114, v0
	v_mov_b32_e32 v115, v0
	v_mov_b32_e32 v116, v0
	v_mov_b32_e32 v117, v0
	v_mov_b32_e32 v118, v0
	v_mov_b32_e32 v119, v0
	v_mov_b32_e32 v128, v0
	v_mov_b32_e32 v129, v0
	v_mov_b32_e32 v130, v0
	v_mov_b32_e32 v131, v0
	v_mov_b32_e32 v132, v0
	v_mov_b32_e32 v133, v0
	v_mov_b32_e32 v134, v0
	v_mov_b32_e32 v135, v0
	v_mov_b32_e32 v76, v0
	v_mov_b32_e32 v77, v0
	v_mov_b32_e32 v78, v0
	v_mov_b32_e32 v79, v0
	v_mov_b32_e32 v80, v0
	v_mov_b32_e32 v81, v0
	v_mov_b32_e32 v82, v0
	v_mov_b32_e32 v83, v0
	v_mov_b32_e32 v104, v0
	v_mov_b32_e32 v105, v0
	v_mov_b32_e32 v106, v0
	v_mov_b32_e32 v107, v0
	v_mov_b32_e32 v108, v0
	v_mov_b32_e32 v109, v0
	v_mov_b32_e32 v110, v0
	v_mov_b32_e32 v111, v0
	v_mov_b32_e32 v120, v0
	v_mov_b32_e32 v121, v0
	v_mov_b32_e32 v122, v0
	v_mov_b32_e32 v123, v0
	v_mov_b32_e32 v124, v0
	v_mov_b32_e32 v125, v0
	v_mov_b32_e32 v126, v0
	v_mov_b32_e32 v127, v0
	v_mov_b32_e32 v136, v0
	v_mov_b32_e32 v137, v0
	v_mov_b32_e32 v138, v0
	v_mov_b32_e32 v139, v0
	v_mov_b32_e32 v140, v0
	v_mov_b32_e32 v141, v0
	v_mov_b32_e32 v142, v0
	v_mov_b32_e32 v143, v0
	.p2align 6

; template <class Epi, class Sched, bool ALIGN_EPI = false, bool SP2 = false>
; __device__ __forceinline__ void gemm_phase(PG8_LAS unsigned char* lds, const Gemm g, const Sched& S, const Epi& E) {
;     ...
;         for (int t = 0; t < nt; t += 2) {
;             const bool last = (t == nt - 2);
;             const char* a1 = cA + (size_t)(t + 1) * kstep;
;             const char* a2 = last ? nA : cA + (size_t)(t + 2) * kstep; const char* b2 = last ? nB : cB + (size_t)(t + 2) * kstep;
;             const char* a3 = a2 + kstep; const char* b3 = b2 + kstep;
;     ...
;         for (int a = 0; a < 2; ++a)
; #pragma unroll
;             for (int b = 0; b < 2; ++b)
; #pragma unroll
;                 for (int m = 0; m < 4; ++m)
; #pragma unroll
;                     for (int n = 0; n < 2; ++n) acc[a][b][m][n] = (f32x4){0.f, 0.f, 0.f, 0.f};
;         cur = nxt; cA = nA; cB = nB; ++ui;
.LBB0_1625:
	v_mov_b32_e32 v127, 0
	s_andn2_b64 vcc, exec, s[16:17]
	v_mov_b32_e32 v126, v127
	v_mov_b32_e32 v125, v127
	v_mov_b32_e32 v124, v127
	v_mov_b32_e32 v123, v127
	v_mov_b32_e32 v122, v127
	v_mov_b32_e32 v121, v127
	v_mov_b32_e32 v120, v127
	v_mov_b32_e32 v111, v127
	v_mov_b32_e32 v110, v127
	v_mov_b32_e32 v109, v127
	v_mov_b32_e32 v108, v127
	v_mov_b32_e32 v107, v127
	v_mov_b32_e32 v106, v127
	v_mov_b32_e32 v105, v127
	v_mov_b32_e32 v104, v127
	v_mov_b32_e32 v95, v127
	v_mov_b32_e32 v94, v127
	v_mov_b32_e32 v93, v127
	v_mov_b32_e32 v92, v127
	v_mov_b32_e32 v91, v127
	v_mov_b32_e32 v90, v127
	v_mov_b32_e32 v89, v127
	v_mov_b32_e32 v88, v127
	v_mov_b32_e32 v79, v127
	v_mov_b32_e32 v78, v127
	v_mov_b32_e32 v77, v127
	v_mov_b32_e32 v76, v127
	v_mov_b32_e32 v75, v127
	v_mov_b32_e32 v74, v127
	v_mov_b32_e32 v73, v127
	v_mov_b32_e32 v72, v127
	v_mov_b32_e32 v119, v127
	v_mov_b32_e32 v118, v127
	v_mov_b32_e32 v117, v127
	v_mov_b32_e32 v116, v127
	v_mov_b32_e32 v115, v127
	v_mov_b32_e32 v114, v127
	v_mov_b32_e32 v113, v127
	v_mov_b32_e32 v112, v127
	v_mov_b32_e32 v103, v127
	v_mov_b32_e32 v102, v127
	v_mov_b32_e32 v101, v127
	v_mov_b32_e32 v100, v127
	v_mov_b32_e32 v99, v127
	v_mov_b32_e32 v98, v127
	v_mov_b32_e32 v97, v127
	v_mov_b32_e32 v96, v127
	v_mov_b32_e32 v87, v127
	v_mov_b32_e32 v86, v127
	v_mov_b32_e32 v85, v127
	v_mov_b32_e32 v84, v127
	v_mov_b32_e32 v83, v127
	v_mov_b32_e32 v82, v127
	v_mov_b32_e32 v81, v127
	v_mov_b32_e32 v80, v127
	v_mov_b32_e32 v71, v127
	v_mov_b32_e32 v70, v127
	v_mov_b32_e32 v69, v127
	v_mov_b32_e32 v68, v127
	v_mov_b32_e32 v67, v127
	v_mov_b32_e32 v66, v127
	v_mov_b32_e32 v65, v127
	v_mov_b32_e32 v64, v127
	v_mov_b32_e32 v63, v127
	v_mov_b32_e32 v62, v127
	v_mov_b32_e32 v61, v127
	v_mov_b32_e32 v60, v127
	v_mov_b32_e32 v59, v127
	v_mov_b32_e32 v58, v127
	v_mov_b32_e32 v57, v127
	v_mov_b32_e32 v56, v127
	v_mov_b32_e32 v47, v127
	v_mov_b32_e32 v46, v127
	v_mov_b32_e32 v45, v127
	v_mov_b32_e32 v44, v127
	v_mov_b32_e32 v43, v127
	v_mov_b32_e32 v42, v127
	v_mov_b32_e32 v41, v127
	v_mov_b32_e32 v40, v127
	v_mov_b32_e32 v31, v127
	v_mov_b32_e32 v30, v127
	v_mov_b32_e32 v29, v127
	v_mov_b32_e32 v28, v127
	v_mov_b32_e32 v27, v127
	v_mov_b32_e32 v26, v127
	v_mov_b32_e32 v25, v127
	v_mov_b32_e32 v24, v127
	v_mov_b32_e32 v15, v127
	v_mov_b32_e32 v14, v127
	v_mov_b32_e32 v13, v127
	v_mov_b32_e32 v12, v127
	v_mov_b32_e32 v11, v127
	v_mov_b32_e32 v10, v127
	v_mov_b32_e32 v9, v127
	v_mov_b32_e32 v8, v127
	v_mov_b32_e32 v55, v127
	v_mov_b32_e32 v54, v127
	v_mov_b32_e32 v53, v127
	v_mov_b32_e32 v52, v127
	v_mov_b32_e32 v51, v127
	v_mov_b32_e32 v50, v127
	v_mov_b32_e32 v49, v127
	v_mov_b32_e32 v48, v127
	v_mov_b32_e32 v39, v127
	v_mov_b32_e32 v38, v127
	v_mov_b32_e32 v37, v127
	v_mov_b32_e32 v36, v127
	v_mov_b32_e32 v35, v127
	v_mov_b32_e32 v34, v127
	v_mov_b32_e32 v33, v127
	v_mov_b32_e32 v32, v127
	v_mov_b32_e32 v23, v127
	v_mov_b32_e32 v22, v127
	v_mov_b32_e32 v21, v127
	v_mov_b32_e32 v20, v127
	v_mov_b32_e32 v19, v127
	v_mov_b32_e32 v18, v127
	v_mov_b32_e32 v17, v127
	v_mov_b32_e32 v16, v127
	v_mov_b32_e32 v7, v127
	v_mov_b32_e32 v6, v127
	v_mov_b32_e32 v5, v127
	v_mov_b32_e32 v4, v127
	v_mov_b32_e32 v3, v127
	v_mov_b32_e32 v2, v127
	v_mov_b32_e32 v1, v127
	v_mov_b32_e32 v0, v127
	s_cbranch_vccnz .LBB0_1628
	s_add_u32 s54, s24, 0x100
	s_addc_u32 s55, s25, 0
	s_add_u32 s4, s26, 0x80
	v_mov_b32_e32 v0, 0
	s_addc_u32 s5, s27, 0
	s_mov_b32 s24, 0
	v_mov_b32_e32 v1, v0
	v_mov_b32_e32 v2, v0
	v_mov_b32_e32 v3, v0
	v_mov_b32_e32 v4, v0
	v_mov_b32_e32 v5, v0
	v_mov_b32_e32 v6, v0
	v_mov_b32_e32 v7, v0
	v_mov_b32_e32 v16, v0
	v_mov_b32_e32 v17, v0
	v_mov_b32_e32 v18, v0
	v_mov_b32_e32 v19, v0
	v_mov_b32_e32 v20, v0
	v_mov_b32_e32 v21, v0
	v_mov_b32_e32 v22, v0
	v_mov_b32_e32 v23, v0
	v_mov_b32_e32 v32, v0
	v_mov_b32_e32 v33, v0
	v_mov_b32_e32 v34, v0
	v_mov_b32_e32 v35, v0
	v_mov_b32_e32 v36, v0
	v_mov_b32_e32 v37, v0
	v_mov_b32_e32 v38, v0
	v_mov_b32_e32 v39, v0
	v_mov_b32_e32 v48, v0
	v_mov_b32_e32 v49, v0
	v_mov_b32_e32 v50, v0
	v_mov_b32_e32 v51, v0
	v_mov_b32_e32 v52, v0
	v_mov_b32_e32 v53, v0
	v_mov_b32_e32 v54, v0
	v_mov_b32_e32 v55, v0
	v_mov_b32_e32 v8, v0
	v_mov_b32_e32 v9, v0
	v_mov_b32_e32 v10, v0
	v_mov_b32_e32 v11, v0
	v_mov_b32_e32 v12, v0
	v_mov_b32_e32 v13, v0
	v_mov_b32_e32 v14, v0
	v_mov_b32_e32 v15, v0
	v_mov_b32_e32 v24, v0
	v_mov_b32_e32 v25, v0
	v_mov_b32_e32 v26, v0
	v_mov_b32_e32 v27, v0
	v_mov_b32_e32 v28, v0
	v_mov_b32_e32 v29, v0
	v_mov_b32_e32 v30, v0
	v_mov_b32_e32 v31, v0
	v_mov_b32_e32 v40, v0
	v_mov_b32_e32 v41, v0
	v_mov_b32_e32 v42, v0
	v_mov_b32_e32 v43, v0
	v_mov_b32_e32 v44, v0
	v_mov_b32_e32 v45, v0
	v_mov_b32_e32 v46, v0
	v_mov_b32_e32 v47, v0
	v_mov_b32_e32 v56, v0
	v_mov_b32_e32 v57, v0
	v_mov_b32_e32 v58, v0
	v_mov_b32_e32 v59, v0
	v_mov_b32_e32 v60, v0
	v_mov_b32_e32 v61, v0
	v_mov_b32_e32 v62, v0
	v_mov_b32_e32 v63, v0
	v_mov_b32_e32 v64, v0
	v_mov_b32_e32 v65, v0
	v_mov_b32_e32 v66, v0
	v_mov_b32_e32 v67, v0
	v_mov_b32_e32 v68, v0
	v_mov_b32_e32 v69, v0
	v_mov_b32_e32 v70, v0
	v_mov_b32_e32 v71, v0
	v_mov_b32_e32 v80, v0
	v_mov_b32_e32 v81, v0
	v_mov_b32_e32 v82, v0
	v_mov_b32_e32 v83, v0
	v_mov_b32_e32 v84, v0
	v_mov_b32_e32 v85, v0
	v_mov_b32_e32 v86, v0
	v_mov_b32_e32 v87, v0
	v_mov_b32_e32 v96, v0
	v_mov_b32_e32 v97, v0
	v_mov_b32_e32 v98, v0
	v_mov_b32_e32 v99, v0
	v_mov_b32_e32 v100, v0
	v_mov_b32_e32 v101, v0
	v_mov_b32_e32 v102, v0
	v_mov_b32_e32 v103, v0
	v_mov_b32_e32 v112, v0
	v_mov_b32_e32 v113, v0
	v_mov_b32_e32 v114, v0
	v_mov_b32_e32 v115, v0
	v_mov_b32_e32 v116, v0
	v_mov_b32_e32 v117, v0
	v_mov_b32_e32 v118, v0
	v_mov_b32_e32 v119, v0
	v_mov_b32_e32 v72, v0
	v_mov_b32_e32 v73, v0
	v_mov_b32_e32 v74, v0
	v_mov_b32_e32 v75, v0
	v_mov_b32_e32 v76, v0
	v_mov_b32_e32 v77, v0
	v_mov_b32_e32 v78, v0
	v_mov_b32_e32 v79, v0
	v_mov_b32_e32 v88, v0
	v_mov_b32_e32 v89, v0
	v_mov_b32_e32 v90, v0
	v_mov_b32_e32 v91, v0
	v_mov_b32_e32 v92, v0
	v_mov_b32_e32 v93, v0
	v_mov_b32_e32 v94, v0
	v_mov_b32_e32 v95, v0
	v_mov_b32_e32 v104, v0
	v_mov_b32_e32 v105, v0
	v_mov_b32_e32 v106, v0
	v_mov_b32_e32 v107, v0
	v_mov_b32_e32 v108, v0
	v_mov_b32_e32 v109, v0
	v_mov_b32_e32 v110, v0
	v_mov_b32_e32 v111, v0
	v_mov_b32_e32 v120, v0
	v_mov_b32_e32 v121, v0
	v_mov_b32_e32 v122, v0
	v_mov_b32_e32 v123, v0
	v_mov_b32_e32 v124, v0
	v_mov_b32_e32 v125, v0
	v_mov_b32_e32 v126, v0
	v_mov_b32_e32 v127, v0
	.p2align 6

; template <class Epi, class Sched, bool ALIGN_EPI = false, bool SP2 = false>
; __device__ __forceinline__ void gemm_phase(PG8_LAS unsigned char* lds, const Gemm g, const Sched& S, const Epi& E) {
;     ...
;         const char* nA = has_next ? (const char*)g.A + (size_t)nxt.pm * tstep : cA; const char* nB = has_next ? (const char*)g.Bt + (size_t)nxt.pn * tstep : cB;
;         for (int t = 0; t < nt; t += 2) {
;             const bool last = (t == nt - 2);
;             const char* a1 = cA + (size_t)(t + 1) * kstep;
;             const char* a2 = last ? nA : cA + (size_t)(t + 2) * kstep; const char* b2 = last ? nB : cB + (size_t)(t + 2) * kstep;
;             const char* a3 = a2 + kstep; const char* b3 = b2 + kstep;
;     ...
;         for (int a = 0; a < 2; ++a)
; #pragma unroll
;             for (int b = 0; b < 2; ++b)
; #pragma unroll
;                 for (int m = 0; m < 4; ++m)
; #pragma unroll
;                     for (int n = 0; n < 2; ++n) acc[a][b][m][n] = (f32x4){0.f, 0.f, 0.f, 0.f};
.LBB0_1735:
	s_ashr_i32 s23, s22, 31
	s_lshl_b64 s[12:13], s[22:23], 19
	s_add_u32 s24, s28, s12
	s_addc_u32 s25, s29, s13
	s_and_b64 s[12:13], s[4:5], exec
	s_cselect_b32 s12, s25, s39
	s_cselect_b32 s13, s24, s38
	s_ashr_i32 s21, s20, 31
	s_lshl_b64 s[26:27], s[20:21], 19
	s_add_u32 s26, s33, s26
	s_addc_u32 s27, s44, s27
	s_and_b64 s[42:43], s[4:5], exec
	s_cselect_b32 s21, s27, s41
	s_cselect_b32 s23, s26, s40
	s_add_u32 s38, s38, 0x40080
	s_addc_u32 s39, s39, 0
	s_add_u32 s56, s40, 0x100
	v_mov_b32_e32 v0, 0
	s_addc_u32 s57, s41, 0
	s_mov_b32 s58, -2
	s_waitcnt lgkmcnt(0)
	v_mov_b32_e32 v1, v0
	v_mov_b32_e32 v2, v0
	v_mov_b32_e32 v3, v0
	v_mov_b32_e32 v4, v0
	v_mov_b32_e32 v5, v0
	v_mov_b32_e32 v6, v0
	v_mov_b32_e32 v7, v0
	v_mov_b32_e32 v16, v0
	v_mov_b32_e32 v17, v0
	v_mov_b32_e32 v18, v0
	v_mov_b32_e32 v19, v0
	v_mov_b32_e32 v20, v0
	v_mov_b32_e32 v21, v0
	v_mov_b32_e32 v22, v0
	v_mov_b32_e32 v23, v0
	v_mov_b32_e32 v32, v0
	v_mov_b32_e32 v33, v0
	v_mov_b32_e32 v34, v0
	v_mov_b32_e32 v35, v0
	v_mov_b32_e32 v36, v0
	v_mov_b32_e32 v37, v0
	v_mov_b32_e32 v38, v0
	v_mov_b32_e32 v39, v0
	v_mov_b32_e32 v48, v0
	v_mov_b32_e32 v49, v0
	v_mov_b32_e32 v50, v0
	v_mov_b32_e32 v51, v0
	v_mov_b32_e32 v52, v0
	v_mov_b32_e32 v53, v0
	v_mov_b32_e32 v54, v0
	v_mov_b32_e32 v55, v0
	v_mov_b32_e32 v8, v0
	v_mov_b32_e32 v9, v0
	v_mov_b32_e32 v10, v0
	v_mov_b32_e32 v11, v0
	v_mov_b32_e32 v12, v0
	v_mov_b32_e32 v13, v0
	v_mov_b32_e32 v14, v0
	v_mov_b32_e32 v15, v0
	v_mov_b32_e32 v24, v0
	v_mov_b32_e32 v25, v0
	v_mov_b32_e32 v26, v0
	v_mov_b32_e32 v27, v0
	v_mov_b32_e32 v28, v0
	v_mov_b32_e32 v29, v0
	v_mov_b32_e32 v30, v0
	v_mov_b32_e32 v31, v0
	v_mov_b32_e32 v40, v0
	v_mov_b32_e32 v41, v0
	v_mov_b32_e32 v42, v0
	v_mov_b32_e32 v43, v0
	v_mov_b32_e32 v44, v0
	v_mov_b32_e32 v45, v0
	v_mov_b32_e32 v46, v0
	v_mov_b32_e32 v47, v0
	v_mov_b32_e32 v56, v0
	v_mov_b32_e32 v57, v0
	v_mov_b32_e32 v58, v0
	v_mov_b32_e32 v59, v0
	v_mov_b32_e32 v60, v0
	v_mov_b32_e32 v61, v0
	v_mov_b32_e32 v62, v0
	v_mov_b32_e32 v63, v0
	v_mov_b32_e32 v64, v0
	v_mov_b32_e32 v65, v0
	v_mov_b32_e32 v66, v0
	v_mov_b32_e32 v67, v0
	v_mov_b32_e32 v68, v0
	v_mov_b32_e32 v69, v0
	v_mov_b32_e32 v70, v0
	v_mov_b32_e32 v71, v0
	v_mov_b32_e32 v80, v0
	v_mov_b32_e32 v81, v0
	v_mov_b32_e32 v82, v0
	v_mov_b32_e32 v83, v0
	v_mov_b32_e32 v84, v0
	v_mov_b32_e32 v85, v0
	v_mov_b32_e32 v86, v0
	v_mov_b32_e32 v87, v0
	v_mov_b32_e32 v96, v0
	v_mov_b32_e32 v97, v0
	v_mov_b32_e32 v98, v0
	v_mov_b32_e32 v99, v0
	v_mov_b32_e32 v100, v0
	v_mov_b32_e32 v101, v0
	v_mov_b32_e32 v102, v0
	v_mov_b32_e32 v103, v0
	v_mov_b32_e32 v112, v0
	v_mov_b32_e32 v113, v0
	v_mov_b32_e32 v114, v0
	v_mov_b32_e32 v115, v0
	v_mov_b32_e32 v116, v0
	v_mov_b32_e32 v117, v0
	v_mov_b32_e32 v118, v0
	v_mov_b32_e32 v119, v0
	v_mov_b32_e32 v72, v0
	v_mov_b32_e32 v73, v0
	v_mov_b32_e32 v74, v0
	v_mov_b32_e32 v75, v0
	v_mov_b32_e32 v76, v0
	v_mov_b32_e32 v77, v0
	v_mov_b32_e32 v78, v0
	v_mov_b32_e32 v79, v0
	v_mov_b32_e32 v88, v0
	v_mov_b32_e32 v89, v0
	v_mov_b32_e32 v90, v0
	v_mov_b32_e32 v91, v0
	v_mov_b32_e32 v92, v0
	v_mov_b32_e32 v93, v0
	v_mov_b32_e32 v94, v0
	v_mov_b32_e32 v95, v0
	v_mov_b32_e32 v104, v0
	v_mov_b32_e32 v105, v0
	v_mov_b32_e32 v106, v0
	v_mov_b32_e32 v107, v0
	v_mov_b32_e32 v108, v0
	v_mov_b32_e32 v109, v0
	v_mov_b32_e32 v110, v0
	v_mov_b32_e32 v111, v0
	v_mov_b32_e32 v120, v0
	v_mov_b32_e32 v121, v0
	v_mov_b32_e32 v122, v0
	v_mov_b32_e32 v123, v0
	v_mov_b32_e32 v124, v0
	v_mov_b32_e32 v125, v0
	v_mov_b32_e32 v126, v0
	v_mov_b32_e32 v127, v0
	.p2align 6

; template <class Epi, class Sched, bool ALIGN_EPI = false, bool SP2 = false>
; __device__ __forceinline__ void gemm_phase(PG8_LAS unsigned char* lds, const Gemm g, const Sched& S, const Epi& E) {
;     ...
;         const char* nA = has_next ? (const char*)g.A + (size_t)nxt.pm * tstep : cA; const char* nB = has_next ? (const char*)g.Bt + (size_t)nxt.pn * tstep : cB;
;         for (int t = 0; t < nt; t += 2) {
;             const bool last = (t == nt - 2);
;             const char* a1 = cA + (size_t)(t + 1) * kstep;
;             const char* a2 = last ? nA : cA + (size_t)(t + 2) * kstep; const char* b2 = last ? nB : cB + (size_t)(t + 2) * kstep;
;             const char* a3 = a2 + kstep; const char* b3 = b2 + kstep;
;     ...
;         for (int a = 0; a < 2; ++a)
; #pragma unroll
;             for (int b = 0; b < 2; ++b)
; #pragma unroll
;                 for (int m = 0; m < 4; ++m)
; #pragma unroll
;                     for (int n = 0; n < 2; ++n) acc[a][b][m][n] = (f32x4){0.f, 0.f, 0.f, 0.f};
.LBB0_1822:
	s_ashr_i32 s19, s18, 31
	s_lshl_b64 s[12:13], s[18:19], 19
	s_add_u32 s20, s33, s12
	s_addc_u32 s21, s38, s13
	s_and_b64 s[12:13], s[2:3], exec
	s_cselect_b32 s12, s21, s35
	s_cselect_b32 s13, s20, s34
	s_ashr_i32 s17, s16, 31
	s_lshl_b64 s[22:23], s[16:17], 19
	s_add_u32 s22, s39, s22
	s_addc_u32 s23, s40, s23
	s_and_b64 s[36:37], s[2:3], exec
	s_cselect_b32 s17, s23, s27
	s_cselect_b32 s19, s22, s26
	s_add_u32 s56, s26, 0x100
	s_addc_u32 s57, s27, 0
	s_add_u32 s26, s34, 0x40080
	v_mov_b32_e32 v0, 0
	s_addc_u32 s27, s35, 0
	s_mov_b32 s58, -2
	v_mov_b32_e32 v1, v0
	v_mov_b32_e32 v2, v0
	v_mov_b32_e32 v3, v0
	v_mov_b32_e32 v4, v0
	v_mov_b32_e32 v5, v0
	v_mov_b32_e32 v6, v0
	v_mov_b32_e32 v7, v0
	v_mov_b32_e32 v16, v0
	v_mov_b32_e32 v17, v0
	v_mov_b32_e32 v18, v0
	v_mov_b32_e32 v19, v0
	v_mov_b32_e32 v20, v0
	v_mov_b32_e32 v21, v0
	v_mov_b32_e32 v22, v0
	v_mov_b32_e32 v23, v0
	v_mov_b32_e32 v32, v0
	v_mov_b32_e32 v33, v0
	v_mov_b32_e32 v34, v0
	v_mov_b32_e32 v35, v0
	v_mov_b32_e32 v36, v0
	v_mov_b32_e32 v37, v0
	v_mov_b32_e32 v38, v0
	v_mov_b32_e32 v39, v0
	v_mov_b32_e32 v48, v0
	v_mov_b32_e32 v49, v0
	v_mov_b32_e32 v50, v0
	v_mov_b32_e32 v51, v0
	v_mov_b32_e32 v52, v0
	v_mov_b32_e32 v53, v0
	v_mov_b32_e32 v54, v0
	v_mov_b32_e32 v55, v0
	v_mov_b32_e32 v8, v0
	v_mov_b32_e32 v9, v0
	v_mov_b32_e32 v10, v0
	v_mov_b32_e32 v11, v0
	v_mov_b32_e32 v12, v0
	v_mov_b32_e32 v13, v0
	v_mov_b32_e32 v14, v0
	v_mov_b32_e32 v15, v0
	v_mov_b32_e32 v24, v0
	v_mov_b32_e32 v25, v0
	v_mov_b32_e32 v26, v0
	v_mov_b32_e32 v27, v0
	v_mov_b32_e32 v28, v0
	v_mov_b32_e32 v29, v0
	v_mov_b32_e32 v30, v0
	v_mov_b32_e32 v31, v0
	v_mov_b32_e32 v40, v0
	v_mov_b32_e32 v41, v0
	v_mov_b32_e32 v42, v0
	v_mov_b32_e32 v43, v0
	v_mov_b32_e32 v44, v0
	v_mov_b32_e32 v45, v0
	v_mov_b32_e32 v46, v0
	v_mov_b32_e32 v47, v0
	v_mov_b32_e32 v56, v0
	v_mov_b32_e32 v57, v0
	v_mov_b32_e32 v58, v0
	v_mov_b32_e32 v59, v0
	v_mov_b32_e32 v60, v0
	v_mov_b32_e32 v61, v0
	v_mov_b32_e32 v62, v0
	v_mov_b32_e32 v63, v0
	v_mov_b32_e32 v64, v0
	v_mov_b32_e32 v65, v0
	v_mov_b32_e32 v66, v0
	v_mov_b32_e32 v67, v0
	v_mov_b32_e32 v68, v0
	v_mov_b32_e32 v69, v0
	v_mov_b32_e32 v70, v0
	v_mov_b32_e32 v71, v0
	v_mov_b32_e32 v80, v0
	v_mov_b32_e32 v81, v0
	v_mov_b32_e32 v82, v0
	v_mov_b32_e32 v83, v0
	v_mov_b32_e32 v84, v0
	v_mov_b32_e32 v85, v0
	v_mov_b32_e32 v86, v0
	v_mov_b32_e32 v87, v0
	v_mov_b32_e32 v96, v0
	v_mov_b32_e32 v97, v0
	v_mov_b32_e32 v98, v0
	v_mov_b32_e32 v99, v0
	v_mov_b32_e32 v100, v0
	v_mov_b32_e32 v101, v0
	v_mov_b32_e32 v102, v0
	v_mov_b32_e32 v103, v0
	v_mov_b32_e32 v112, v0
	v_mov_b32_e32 v113, v0
	v_mov_b32_e32 v114, v0
	v_mov_b32_e32 v115, v0
	v_mov_b32_e32 v116, v0
	v_mov_b32_e32 v117, v0
	v_mov_b32_e32 v118, v0
	v_mov_b32_e32 v119, v0
	v_mov_b32_e32 v72, v0
	v_mov_b32_e32 v73, v0
	v_mov_b32_e32 v74, v0
	v_mov_b32_e32 v75, v0
	v_mov_b32_e32 v76, v0
	v_mov_b32_e32 v77, v0
	v_mov_b32_e32 v78, v0
	v_mov_b32_e32 v79, v0
	v_mov_b32_e32 v88, v0
	v_mov_b32_e32 v89, v0
	v_mov_b32_e32 v90, v0
	v_mov_b32_e32 v91, v0
	v_mov_b32_e32 v92, v0
	v_mov_b32_e32 v93, v0
	v_mov_b32_e32 v94, v0
	v_mov_b32_e32 v95, v0
	v_mov_b32_e32 v104, v0
	v_mov_b32_e32 v105, v0
	v_mov_b32_e32 v106, v0
	v_mov_b32_e32 v107, v0
	v_mov_b32_e32 v108, v0
	v_mov_b32_e32 v109, v0
	v_mov_b32_e32 v110, v0
	v_mov_b32_e32 v111, v0
	v_mov_b32_e32 v120, v0
	v_mov_b32_e32 v121, v0
	v_mov_b32_e32 v122, v0
	v_mov_b32_e32 v123, v0
	v_mov_b32_e32 v124, v0
	v_mov_b32_e32 v125, v0
	v_mov_b32_e32 v126, v0
	v_mov_b32_e32 v127, v0
	.p2align 6

; template <class Epi, class Sched, bool ALIGN_EPI = false, bool SP2 = false>
; __device__ __forceinline__ void gemm_phase(PG8_LAS unsigned char* lds, const Gemm g, const Sched& S, const Epi& E) {
;     ...
;         for (int t = 0; t < nt; t += 2) {
;             const bool last = (t == nt - 2);
;             const char* a1 = cA + (size_t)(t + 1) * kstep;
;             const char* a2 = last ? nA : cA + (size_t)(t + 2) * kstep; const char* b2 = last ? nB : cB + (size_t)(t + 2) * kstep;
;             const char* a3 = a2 + kstep; const char* b3 = b2 + kstep;
;     ...
;         for (int a = 0; a < 2; ++a)
; #pragma unroll
;             for (int b = 0; b < 2; ++b)
; #pragma unroll
;                 for (int m = 0; m < 4; ++m)
; #pragma unroll
;                     for (int n = 0; n < 2; ++n) acc[a][b][m][n] = (f32x4){0.f, 0.f, 0.f, 0.f};
;         cur = nxt; cA = nA; cB = nB; ++ui;
.LBB0_1901:
	s_add_u32 s51, s24, 0x100
	s_addc_u32 s52, s25, 0
	s_add_u32 s24, s26, 0xb0080
	v_mov_b32_e32 v0, 0
	s_addc_u32 s25, s27, 0
	s_mov_b32 s53, -2
	v_mov_b32_e32 v1, v0
	v_mov_b32_e32 v2, v0
	v_mov_b32_e32 v3, v0
	v_mov_b32_e32 v4, v0
	v_mov_b32_e32 v5, v0
	v_mov_b32_e32 v6, v0
	v_mov_b32_e32 v7, v0
	v_mov_b32_e32 v16, v0
	v_mov_b32_e32 v17, v0
	v_mov_b32_e32 v18, v0
	v_mov_b32_e32 v19, v0
	v_mov_b32_e32 v20, v0
	v_mov_b32_e32 v21, v0
	v_mov_b32_e32 v22, v0
	v_mov_b32_e32 v23, v0
	v_mov_b32_e32 v32, v0
	v_mov_b32_e32 v33, v0
	v_mov_b32_e32 v34, v0
	v_mov_b32_e32 v35, v0
	v_mov_b32_e32 v36, v0
	v_mov_b32_e32 v37, v0
	v_mov_b32_e32 v38, v0
	v_mov_b32_e32 v39, v0
	v_mov_b32_e32 v48, v0
	v_mov_b32_e32 v49, v0
	v_mov_b32_e32 v50, v0
	v_mov_b32_e32 v51, v0
	v_mov_b32_e32 v52, v0
	v_mov_b32_e32 v53, v0
	v_mov_b32_e32 v54, v0
	v_mov_b32_e32 v55, v0
	v_mov_b32_e32 v8, v0
	v_mov_b32_e32 v9, v0
	v_mov_b32_e32 v10, v0
	v_mov_b32_e32 v11, v0
	v_mov_b32_e32 v12, v0
	v_mov_b32_e32 v13, v0
	v_mov_b32_e32 v14, v0
	v_mov_b32_e32 v15, v0
	v_mov_b32_e32 v24, v0
	v_mov_b32_e32 v25, v0
	v_mov_b32_e32 v26, v0
	v_mov_b32_e32 v27, v0
	v_mov_b32_e32 v28, v0
	v_mov_b32_e32 v29, v0
	v_mov_b32_e32 v30, v0
	v_mov_b32_e32 v31, v0
	v_mov_b32_e32 v40, v0
	v_mov_b32_e32 v41, v0
	v_mov_b32_e32 v42, v0
	v_mov_b32_e32 v43, v0
	v_mov_b32_e32 v44, v0
	v_mov_b32_e32 v45, v0
	v_mov_b32_e32 v46, v0
	v_mov_b32_e32 v47, v0
	v_mov_b32_e32 v56, v0
	v_mov_b32_e32 v57, v0
	v_mov_b32_e32 v58, v0
	v_mov_b32_e32 v59, v0
	v_mov_b32_e32 v60, v0
	v_mov_b32_e32 v61, v0
	v_mov_b32_e32 v62, v0
	v_mov_b32_e32 v63, v0
	v_mov_b32_e32 v64, v0
	v_mov_b32_e32 v65, v0
	v_mov_b32_e32 v66, v0
	v_mov_b32_e32 v67, v0
	v_mov_b32_e32 v68, v0
	v_mov_b32_e32 v69, v0
	v_mov_b32_e32 v70, v0
	v_mov_b32_e32 v71, v0
	v_mov_b32_e32 v80, v0
	v_mov_b32_e32 v81, v0
	v_mov_b32_e32 v82, v0
	v_mov_b32_e32 v83, v0
	v_mov_b32_e32 v84, v0
	v_mov_b32_e32 v85, v0
	v_mov_b32_e32 v86, v0
	v_mov_b32_e32 v87, v0
	v_mov_b32_e32 v96, v0
	v_mov_b32_e32 v97, v0
	v_mov_b32_e32 v98, v0
	v_mov_b32_e32 v99, v0
	v_mov_b32_e32 v100, v0
	v_mov_b32_e32 v101, v0
	v_mov_b32_e32 v102, v0
	v_mov_b32_e32 v103, v0
	v_mov_b32_e32 v112, v0
	v_mov_b32_e32 v113, v0
	v_mov_b32_e32 v114, v0
	v_mov_b32_e32 v115, v0
	v_mov_b32_e32 v116, v0
	v_mov_b32_e32 v117, v0
	v_mov_b32_e32 v118, v0
	v_mov_b32_e32 v119, v0
	v_mov_b32_e32 v72, v0
	v_mov_b32_e32 v73, v0
	v_mov_b32_e32 v74, v0
	v_mov_b32_e32 v75, v0
	v_mov_b32_e32 v76, v0
	v_mov_b32_e32 v77, v0
	v_mov_b32_e32 v78, v0
	v_mov_b32_e32 v79, v0
	v_mov_b32_e32 v88, v0
	v_mov_b32_e32 v89, v0
	v_mov_b32_e32 v90, v0
	v_mov_b32_e32 v91, v0
	v_mov_b32_e32 v92, v0
	v_mov_b32_e32 v93, v0
	v_mov_b32_e32 v94, v0
	v_mov_b32_e32 v95, v0
	v_mov_b32_e32 v104, v0
	v_mov_b32_e32 v105, v0
	v_mov_b32_e32 v106, v0
	v_mov_b32_e32 v107, v0
	v_mov_b32_e32 v108, v0
	v_mov_b32_e32 v109, v0
	v_mov_b32_e32 v110, v0
	v_mov_b32_e32 v111, v0
	v_mov_b32_e32 v120, v0
	v_mov_b32_e32 v121, v0
	v_mov_b32_e32 v122, v0
	v_mov_b32_e32 v123, v0
	v_mov_b32_e32 v124, v0
	v_mov_b32_e32 v125, v0
	v_mov_b32_e32 v126, v0
	v_mov_b32_e32 v127, v0
	.p2align 6
